# merge gate passes: bias loads and the first two branch-product gather groups issued in the GEMM tail into tail-dead registers (epilogue starts with data in flight)
# speedup vs baseline: 1.0134x; 1.0034x over previous
; #define G_LDA(dst, b, h)                                                                                                  \
;   _Pragma("unroll") for (int m = 0; m < 4; ++m) _Pragma("unroll") for (int k = 0; k < 2; ++k)                             \
;       dst[m][k] = *(const bf16x8*)((const char*)G_SA(b, h) + ((wr * 4 + m) * 2 + k) * 1024 + rdo)
; #define G_LDB(dst, b, h)                                                                                                  \
;   _Pragma("unroll") for (int n = 0; n < 2; ++n) _Pragma("unroll") for (int k = 0; k < 2; ++k)                             \
;       dst[n][k] = *(const bf16x8*)((const char*)G_SB(b, h) + ((wc * 2 + n) * 2 + k) * 1024 + rdo)
; #define G_WAIT_V(n) asm volatile("s_waitcnt vmcnt(" #n ")" ::: "memory")
; #define G_WAIT_L(n) asm volatile("s_waitcnt lgkmcnt(" #n ")" ::: "memory")
; #define G_BAR __builtin_amdgcn_s_barrier()
; #define G_SCHED __builtin_amdgcn_sched_barrier(0)
; DI void br_flush(PREF p, f32x4 (&acc)[2][2][4][2], int slot) { br_store(p, acc, slot); zero_acc256(acc); }
;     ...
;   for (int tt = 0; tt < nt - 2; tt += 2) {
;     G_LDB(B0, 0, 0); G_SCHED; G_LDA(At, 0, 0); G_STAGE(G_SA(1, 1), A, oa0, oa1, LDA, 128, KA(tt + 1));
;     G_WAIT_L(8); G_BAR; G_WAIT_L(0); G_MMA(0, 0, At, B0); G_BAR; G_SCHED;
;     G_LDB(B1, 0, 1); G_STAGE(G_SB(0, 0), B, ob0, ob1, LDB, 0, KB(tt + 2));
;     G_BAR; G_WAIT_L(0); G_MMA(0, 1, At, B1); G_BAR;
;     G_LDA(At, 0, 1); G_STAGE(G_SA(0, 0), A, oa0, oa1, LDA, 0, KA(tt + 2));
;     G_BAR; G_WAIT_L(0); G_MMA(1, 0, At, B0); G_BAR; G_SCHED;
;     G_STAGE(G_SB(0, 1), B, ob0, ob1, LDB, 128, KB(tt + 2));
;     G_WAIT_V(6); G_BAR; G_MMA(1, 1, At, B1); G_BAR;
;     G_LDB(B0, 1, 0); G_SCHED; G_LDA(At, 1, 0); G_STAGE(G_SA(0, 1), A, oa0, oa1, LDA, 128, KA(tt + 2));
;     G_WAIT_L(8); G_BAR; G_WAIT_L(0); G_MMA(0, 0, At, B0); G_BAR; G_SCHED;
;     G_LDB(B1, 1, 1); G_STAGE(G_SB(1, 0), B, ob0, ob1, LDB, 0, KB(tt + 3));
;     G_BAR; G_WAIT_L(0); G_MMA(0, 1, At, B1); G_BAR;
;     G_LDA(At, 1, 1); G_STAGE(G_SA(1, 0), A, oa0, oa1, LDA, 0, KA(tt + 3));
;     G_BAR; G_WAIT_L(0); G_MMA(1, 0, At, B0); G_BAR; G_SCHED;
;     G_STAGE(G_SB(1, 1), B, ob0, ob1, LDB, 128, KB(tt + 3));
;     G_WAIT_V(6); G_BAR; G_MMA(1, 1, At, B1); G_BAR;
;     if (MODE && ((tt + 1) & 3) == 3) br_flush(p, acc, (tt + 1) >> 2);
;   }
.LBB0_105:
	ds_read_b128 v[164:167], v160
	ds_read_b128 v[182:185], v160 offset:1024
	ds_read_b128 v[186:189], v160 offset:2048
	ds_read_b128 v[190:193], v160 offset:3072
	v_add_u32_e32 v161, 0xc000, v143
	v_lshl_add_u64 v[242:243], v[136:137], 0, s[8:9]
	v_readfirstlane_b32 s0, v161
	v_add_u32_e32 v162, 0xe000, v143
	v_lshl_add_u64 v[226:227], v[242:243], 0, s[78:79]
	s_mov_b32 m0, s0
	v_lshl_add_u64 v[244:245], v[134:135], 0, s[8:9]
	v_readfirstlane_b32 s0, v162
	ds_read_b128 v[194:197], v142
	ds_read_b128 v[198:201], v142 offset:1024
	ds_read_b128 v[202:205], v142 offset:2048
	ds_read_b128 v[206:209], v142 offset:3072
	ds_read_b128 v[210:213], v142 offset:4096
	ds_read_b128 v[214:217], v142 offset:5120
	ds_read_b128 v[218:221], v142 offset:6144
	ds_read_b128 v[222:225], v142 offset:7168
	global_load_lds_dwordx4 v[226:227], off
	v_lshl_add_u64 v[226:227], v[244:245], 0, s[78:79]
	s_mov_b32 m0, s0
	s_nop 0
	global_load_lds_dwordx4 v[226:227], off
	s_waitcnt lgkmcnt(8)
	s_barrier
	s_waitcnt lgkmcnt(0)
	s_setprio 1
	s_waitcnt lgkmcnt(0)
	v_mfma_f32_16x16x32_bf16 v[126:129], v[194:197], v[164:167], v[126:129]
	v_mfma_f32_16x16x32_bf16 v[122:125], v[194:197], v[186:189], v[122:125]
	v_mfma_f32_16x16x32_bf16 v[118:121], v[202:205], v[164:167], v[118:121]
	v_mfma_f32_16x16x32_bf16 v[114:117], v[202:205], v[186:189], v[114:117]
	v_mfma_f32_16x16x32_bf16 v[110:113], v[210:213], v[164:167], v[110:113]
	v_mfma_f32_16x16x32_bf16 v[106:109], v[210:213], v[186:189], v[106:109]
	v_mfma_f32_16x16x32_bf16 v[102:105], v[218:221], v[164:167], v[102:105]
	v_mfma_f32_16x16x32_bf16 v[98:101], v[218:221], v[186:189], v[98:101]
	v_mfma_f32_16x16x32_bf16 v[126:129], v[198:201], v[182:185], v[126:129]
	v_mfma_f32_16x16x32_bf16 v[122:125], v[198:201], v[190:193], v[122:125]
	v_mfma_f32_16x16x32_bf16 v[118:121], v[206:209], v[182:185], v[118:121]
	v_mfma_f32_16x16x32_bf16 v[114:117], v[206:209], v[190:193], v[114:117]
	v_mfma_f32_16x16x32_bf16 v[110:113], v[214:217], v[182:185], v[110:113]
	v_mfma_f32_16x16x32_bf16 v[106:109], v[214:217], v[190:193], v[106:109]
	v_mfma_f32_16x16x32_bf16 v[102:105], v[222:225], v[182:185], v[102:105]
	v_mfma_f32_16x16x32_bf16 v[98:101], v[222:225], v[190:193], v[98:101]
	s_setprio 0
	s_barrier
	v_lshl_add_u64 v[246:247], v[140:141], 0, s[8:9]
	v_readfirstlane_b32 s0, v146
	v_lshl_add_u64 v[248:249], v[246:247], 0, s[50:51]
	s_mov_b32 m0, s0
	ds_read_b128 v[226:229], v158
	ds_read_b128 v[230:233], v158 offset:1024
	ds_read_b128 v[234:237], v158 offset:2048
	ds_read_b128 v[238:241], v158 offset:3072
	global_load_lds_dwordx4 v[248:249], off
	v_lshl_add_u64 v[248:249], v[138:139], 0, s[8:9]
	v_readfirstlane_b32 s0, v147
	v_lshl_add_u64 v[250:251], v[248:249], 0, s[50:51]
	s_mov_b32 m0, s0
	s_nop 0
	global_load_lds_dwordx4 v[250:251], off
	s_barrier
	s_waitcnt lgkmcnt(0)
	s_setprio 1
	s_waitcnt lgkmcnt(0)
	v_mfma_f32_16x16x32_bf16 v[94:97], v[194:197], v[226:229], v[94:97]
	v_mfma_f32_16x16x32_bf16 v[90:93], v[194:197], v[234:237], v[90:93]
	v_mfma_f32_16x16x32_bf16 v[86:89], v[202:205], v[226:229], v[86:89]
	v_mfma_f32_16x16x32_bf16 v[82:85], v[202:205], v[234:237], v[82:85]
	v_mfma_f32_16x16x32_bf16 v[78:81], v[210:213], v[226:229], v[78:81]
	v_mfma_f32_16x16x32_bf16 v[74:77], v[210:213], v[234:237], v[74:77]
	v_mfma_f32_16x16x32_bf16 v[70:73], v[218:221], v[226:229], v[70:73]
	v_mfma_f32_16x16x32_bf16 v[66:69], v[218:221], v[234:237], v[66:69]
	v_mfma_f32_16x16x32_bf16 v[94:97], v[198:201], v[230:233], v[94:97]
	v_mfma_f32_16x16x32_bf16 v[90:93], v[198:201], v[238:241], v[90:93]
	v_mfma_f32_16x16x32_bf16 v[86:89], v[206:209], v[230:233], v[86:89]
	v_mfma_f32_16x16x32_bf16 v[82:85], v[206:209], v[238:241], v[82:85]
	v_mfma_f32_16x16x32_bf16 v[78:81], v[214:217], v[230:233], v[78:81]
	v_mfma_f32_16x16x32_bf16 v[74:77], v[214:217], v[238:241], v[74:77]
	v_mfma_f32_16x16x32_bf16 v[70:73], v[222:225], v[230:233], v[70:73]
	v_mfma_f32_16x16x32_bf16 v[66:69], v[222:225], v[238:241], v[66:69]
	s_setprio 0
	v_readfirstlane_b32 s0, v143
	v_lshl_add_u64 v[250:251], v[242:243], 0, s[82:83]
	s_mov_b32 m0, s0
	v_readfirstlane_b32 s0, v144
	s_barrier
	ds_read_b128 v[194:197], v142 offset:16384
	ds_read_b128 v[198:201], v142 offset:17408
	ds_read_b128 v[202:205], v142 offset:18432
	ds_read_b128 v[206:209], v142 offset:19456
	ds_read_b128 v[210:213], v142 offset:20480
	ds_read_b128 v[214:217], v142 offset:21504
	ds_read_b128 v[218:221], v142 offset:22528
	ds_read_b128 v[222:225], v142 offset:23552
	global_load_lds_dwordx4 v[250:251], off
	v_lshl_add_u64 v[250:251], v[244:245], 0, s[82:83]
	s_mov_b32 m0, s0
	s_nop 0
	global_load_lds_dwordx4 v[250:251], off
	s_barrier
	s_waitcnt lgkmcnt(0)
	s_setprio 1
	s_waitcnt lgkmcnt(0)
	v_mfma_f32_16x16x32_bf16 v[62:65], v[194:197], v[164:167], v[62:65]
	v_mfma_f32_16x16x32_bf16 v[58:61], v[194:197], v[186:189], v[58:61]
	v_mfma_f32_16x16x32_bf16 v[54:57], v[202:205], v[164:167], v[54:57]
	v_mfma_f32_16x16x32_bf16 v[50:53], v[202:205], v[186:189], v[50:53]
	v_mfma_f32_16x16x32_bf16 v[46:49], v[210:213], v[164:167], v[46:49]
	v_mfma_f32_16x16x32_bf16 v[42:45], v[210:213], v[186:189], v[42:45]
	v_mfma_f32_16x16x32_bf16 v[38:41], v[218:221], v[164:167], v[38:41]
	v_mfma_f32_16x16x32_bf16 v[34:37], v[218:221], v[186:189], v[34:37]
	v_mfma_f32_16x16x32_bf16 v[62:65], v[198:201], v[182:185], v[62:65]
	v_mfma_f32_16x16x32_bf16 v[58:61], v[198:201], v[190:193], v[58:61]
	v_mfma_f32_16x16x32_bf16 v[54:57], v[206:209], v[182:185], v[54:57]
	v_mfma_f32_16x16x32_bf16 v[50:53], v[206:209], v[190:193], v[50:53]
	v_mfma_f32_16x16x32_bf16 v[46:49], v[214:217], v[182:185], v[46:49]
	v_mfma_f32_16x16x32_bf16 v[42:45], v[214:217], v[190:193], v[42:45]
	v_mfma_f32_16x16x32_bf16 v[38:41], v[222:225], v[182:185], v[38:41]
	v_mfma_f32_16x16x32_bf16 v[34:37], v[222:225], v[190:193], v[34:37]
	s_setprio 0
	s_barrier
; #define G_LDA(dst, b, h)                                                                                                  \
;   _Pragma("unroll") for (int m = 0; m < 4; ++m) _Pragma("unroll") for (int k = 0; k < 2; ++k)                             \
;       dst[m][k] = *(const bf16x8*)((const char*)G_SA(b, h) + ((wr * 4 + m) * 2 + k) * 1024 + rdo)
; #define G_LDB(dst, b, h)                                                                                                  \
;   _Pragma("unroll") for (int n = 0; n < 2; ++n) _Pragma("unroll") for (int k = 0; k < 2; ++k)                             \
;       dst[n][k] = *(const bf16x8*)((const char*)G_SB(b, h) + ((wc * 2 + n) * 2 + k) * 1024 + rdo)
; #define G_WAIT_V(n) asm volatile("s_waitcnt vmcnt(" #n ")" ::: "memory")
; #define G_WAIT_L(n) asm volatile("s_waitcnt lgkmcnt(" #n ")" ::: "memory")
; #define G_BAR __builtin_amdgcn_s_barrier()
; #define G_SCHED __builtin_amdgcn_sched_barrier(0)
; DI void br_flush(PREF p, f32x4 (&acc)[2][2][4][2], int slot) { br_store(p, acc, slot); zero_acc256(acc); }
;     ...
;   for (int tt = 0; tt < nt - 2; tt += 2) {
;     G_LDB(B0, 0, 0); G_SCHED; G_LDA(At, 0, 0); G_STAGE(G_SA(1, 1), A, oa0, oa1, LDA, 128, KA(tt + 1));
;     G_WAIT_L(8); G_BAR; G_WAIT_L(0); G_MMA(0, 0, At, B0); G_BAR; G_SCHED;
;     G_LDB(B1, 0, 1); G_STAGE(G_SB(0, 0), B, ob0, ob1, LDB, 0, KB(tt + 2));
;     G_BAR; G_WAIT_L(0); G_MMA(0, 1, At, B1); G_BAR;
;     G_LDA(At, 0, 1); G_STAGE(G_SA(0, 0), A, oa0, oa1, LDA, 0, KA(tt + 2));
;     G_BAR; G_WAIT_L(0); G_MMA(1, 0, At, B0); G_BAR; G_SCHED;
;     G_STAGE(G_SB(0, 1), B, ob0, ob1, LDB, 128, KB(tt + 2));
;     G_WAIT_V(6); G_BAR; G_MMA(1, 1, At, B1); G_BAR;
;     G_LDB(B0, 1, 0); G_SCHED; G_LDA(At, 1, 0); G_STAGE(G_SA(0, 1), A, oa0, oa1, LDA, 128, KA(tt + 2));
;     G_WAIT_L(8); G_BAR; G_WAIT_L(0); G_MMA(0, 0, At, B0); G_BAR; G_SCHED;
;     G_LDB(B1, 1, 1); G_STAGE(G_SB(1, 0), B, ob0, ob1, LDB, 0, KB(tt + 3));
;     G_BAR; G_WAIT_L(0); G_MMA(0, 1, At, B1); G_BAR;
;     G_LDA(At, 1, 1); G_STAGE(G_SA(1, 0), A, oa0, oa1, LDA, 0, KA(tt + 3));
;     G_BAR; G_WAIT_L(0); G_MMA(1, 0, At, B0); G_BAR; G_SCHED;
;     G_STAGE(G_SB(1, 1), B, ob0, ob1, LDB, 128, KB(tt + 3));
;     G_WAIT_V(6); G_BAR; G_MMA(1, 1, At, B1); G_BAR;
;     if (MODE && ((tt + 1) & 3) == 3) br_flush(p, acc, (tt + 1) >> 2);
;   }
	v_readfirstlane_b32 s0, v149
	v_lshl_add_u64 v[164:165], v[246:247], 0, s[38:39]
	s_mov_b32 m0, s0
	v_readfirstlane_b32 s0, v150
	global_load_lds_dwordx4 v[164:165], off
	v_lshl_add_u64 v[164:165], v[248:249], 0, s[38:39]
	s_mov_b32 m0, s0
	s_nop 0
	global_load_lds_dwordx4 v[164:165], off
	s_waitcnt vmcnt(6)
	s_barrier
	s_setprio 1
	v_mfma_f32_16x16x32_bf16 v[30:33], v[194:197], v[226:229], v[30:33]
	v_mfma_f32_16x16x32_bf16 v[26:29], v[194:197], v[234:237], v[26:29]
	v_mfma_f32_16x16x32_bf16 v[22:25], v[202:205], v[226:229], v[22:25]
	v_mfma_f32_16x16x32_bf16 v[18:21], v[202:205], v[234:237], v[18:21]
	v_mfma_f32_16x16x32_bf16 v[14:17], v[210:213], v[226:229], v[14:17]
	v_mfma_f32_16x16x32_bf16 v[10:13], v[210:213], v[234:237], v[10:13]
	v_mfma_f32_16x16x32_bf16 v[6:9], v[218:221], v[226:229], v[6:9]
	v_mfma_f32_16x16x32_bf16 v[2:5], v[218:221], v[234:237], v[2:5]
	v_mfma_f32_16x16x32_bf16 v[30:33], v[198:201], v[230:233], v[30:33]
	v_mfma_f32_16x16x32_bf16 v[26:29], v[198:201], v[238:241], v[26:29]
	v_mfma_f32_16x16x32_bf16 v[22:25], v[206:209], v[230:233], v[22:25]
	v_mfma_f32_16x16x32_bf16 v[18:21], v[206:209], v[238:241], v[18:21]
	v_mfma_f32_16x16x32_bf16 v[14:17], v[214:217], v[230:233], v[14:17]
	v_mfma_f32_16x16x32_bf16 v[10:13], v[214:217], v[238:241], v[10:13]
	v_mfma_f32_16x16x32_bf16 v[6:9], v[222:225], v[230:233], v[6:9]
	v_mfma_f32_16x16x32_bf16 v[2:5], v[222:225], v[238:241], v[2:5]
	s_setprio 0
	s_barrier
	ds_read_b128 v[164:167], v148
	ds_read_b128 v[182:185], v148 offset:1024
	ds_read_b128 v[186:189], v148 offset:2048
	ds_read_b128 v[190:193], v148 offset:3072
	v_readfirstlane_b32 s0, v151
	v_lshl_add_u64 v[226:227], v[242:243], 0, s[86:87]
	s_mov_b32 m0, s0
	v_readfirstlane_b32 s0, v152
	ds_read_b128 v[194:197], v142 offset:32768
	ds_read_b128 v[198:201], v142 offset:33792
	ds_read_b128 v[202:205], v142 offset:34816
	ds_read_b128 v[206:209], v142 offset:35840
	ds_read_b128 v[210:213], v142 offset:36864
	ds_read_b128 v[214:217], v142 offset:37888
	ds_read_b128 v[218:221], v142 offset:38912
	ds_read_b128 v[222:225], v142 offset:39936
	global_load_lds_dwordx4 v[226:227], off
	v_lshl_add_u64 v[226:227], v[244:245], 0, s[86:87]
	s_mov_b32 m0, s0
	s_nop 0
	global_load_lds_dwordx4 v[226:227], off
	s_waitcnt lgkmcnt(8)
	s_barrier
	s_waitcnt lgkmcnt(0)
	s_setprio 1
	s_waitcnt lgkmcnt(0)
	v_mfma_f32_16x16x32_bf16 v[126:129], v[194:197], v[164:167], v[126:129]
	v_mfma_f32_16x16x32_bf16 v[122:125], v[194:197], v[186:189], v[122:125]
	v_mfma_f32_16x16x32_bf16 v[118:121], v[202:205], v[164:167], v[118:121]
	v_mfma_f32_16x16x32_bf16 v[114:117], v[202:205], v[186:189], v[114:117]
	v_mfma_f32_16x16x32_bf16 v[110:113], v[210:213], v[164:167], v[110:113]
	v_mfma_f32_16x16x32_bf16 v[106:109], v[210:213], v[186:189], v[106:109]
	v_mfma_f32_16x16x32_bf16 v[102:105], v[218:221], v[164:167], v[102:105]
	v_mfma_f32_16x16x32_bf16 v[98:101], v[218:221], v[186:189], v[98:101]
	v_mfma_f32_16x16x32_bf16 v[126:129], v[198:201], v[182:185], v[126:129]
	v_mfma_f32_16x16x32_bf16 v[122:125], v[198:201], v[190:193], v[122:125]
	v_mfma_f32_16x16x32_bf16 v[118:121], v[206:209], v[182:185], v[118:121]
	v_mfma_f32_16x16x32_bf16 v[114:117], v[206:209], v[190:193], v[114:117]
	v_mfma_f32_16x16x32_bf16 v[110:113], v[214:217], v[182:185], v[110:113]
	v_mfma_f32_16x16x32_bf16 v[106:109], v[214:217], v[190:193], v[106:109]
	v_mfma_f32_16x16x32_bf16 v[102:105], v[222:225], v[182:185], v[102:105]
	v_mfma_f32_16x16x32_bf16 v[98:101], v[222:225], v[190:193], v[98:101]
	s_setprio 0
	s_barrier
	v_readfirstlane_b32 s0, v153
	v_lshl_add_u64 v[250:251], v[246:247], 0, s[4:5]
	s_mov_b32 m0, s0
	v_readfirstlane_b32 s0, v154
	ds_read_b128 v[226:229], v145
	ds_read_b128 v[230:233], v145 offset:1024
	ds_read_b128 v[234:237], v145 offset:2048
	ds_read_b128 v[238:241], v145 offset:3072
	global_load_lds_dwordx4 v[250:251], off
	v_lshl_add_u64 v[250:251], v[248:249], 0, s[4:5]
	s_mov_b32 m0, s0
	s_nop 0
	global_load_lds_dwordx4 v[250:251], off
	s_barrier
	s_waitcnt lgkmcnt(0)
	s_setprio 1
	s_waitcnt lgkmcnt(0)
	v_mfma_f32_16x16x32_bf16 v[94:97], v[194:197], v[226:229], v[94:97]
	v_mfma_f32_16x16x32_bf16 v[90:93], v[194:197], v[234:237], v[90:93]
	v_mfma_f32_16x16x32_bf16 v[86:89], v[202:205], v[226:229], v[86:89]
	v_mfma_f32_16x16x32_bf16 v[82:85], v[202:205], v[234:237], v[82:85]
	v_mfma_f32_16x16x32_bf16 v[78:81], v[210:213], v[226:229], v[78:81]
	v_mfma_f32_16x16x32_bf16 v[74:77], v[210:213], v[234:237], v[74:77]
	v_mfma_f32_16x16x32_bf16 v[70:73], v[218:221], v[226:229], v[70:73]
	v_mfma_f32_16x16x32_bf16 v[66:69], v[218:221], v[234:237], v[66:69]
	v_mfma_f32_16x16x32_bf16 v[94:97], v[198:201], v[230:233], v[94:97]
	v_mfma_f32_16x16x32_bf16 v[90:93], v[198:201], v[238:241], v[90:93]
	v_mfma_f32_16x16x32_bf16 v[86:89], v[206:209], v[230:233], v[86:89]
	v_mfma_f32_16x16x32_bf16 v[82:85], v[206:209], v[238:241], v[82:85]
	v_mfma_f32_16x16x32_bf16 v[78:81], v[214:217], v[230:233], v[78:81]
	v_mfma_f32_16x16x32_bf16 v[74:77], v[214:217], v[238:241], v[74:77]
	v_mfma_f32_16x16x32_bf16 v[70:73], v[222:225], v[230:233], v[70:73]
	v_mfma_f32_16x16x32_bf16 v[66:69], v[222:225], v[238:241], v[66:69]
	s_setprio 0
	v_readfirstlane_b32 s0, v155
	v_lshl_add_u64 v[242:243], v[242:243], 0, s[90:91]
	s_mov_b32 m0, s0
	v_readfirstlane_b32 s0, v156
	s_barrier
	ds_read_b128 v[194:197], v142 offset:49152
	ds_read_b128 v[198:201], v142 offset:50176
	ds_read_b128 v[202:205], v142 offset:51200
	ds_read_b128 v[206:209], v142 offset:52224
	ds_read_b128 v[210:213], v142 offset:53248
	ds_read_b128 v[214:217], v142 offset:54272
	ds_read_b128 v[218:221], v142 offset:55296
	ds_read_b128 v[222:225], v142 offset:56320
	global_load_lds_dwordx4 v[242:243], off
	v_lshl_add_u64 v[242:243], v[244:245], 0, s[90:91]
	s_mov_b32 m0, s0
	s_nop 0
	global_load_lds_dwordx4 v[242:243], off
	s_barrier
; #define G_LDA(dst, b, h)                                                                                                  \
;   _Pragma("unroll") for (int m = 0; m < 4; ++m) _Pragma("unroll") for (int k = 0; k < 2; ++k)                             \
;       dst[m][k] = *(const bf16x8*)((const char*)G_SA(b, h) + ((wr * 4 + m) * 2 + k) * 1024 + rdo)
; #define G_LDB(dst, b, h)                                                                                                  \
;   _Pragma("unroll") for (int n = 0; n < 2; ++n) _Pragma("unroll") for (int k = 0; k < 2; ++k)                             \
;       dst[n][k] = *(const bf16x8*)((const char*)G_SB(b, h) + ((wc * 2 + n) * 2 + k) * 1024 + rdo)
; #define G_WAIT_V(n) asm volatile("s_waitcnt vmcnt(" #n ")" ::: "memory")
; #define G_BAR __builtin_amdgcn_s_barrier()
; DI void br_flush(PREF p, f32x4 (&acc)[2][2][4][2], int slot) { br_store(p, acc, slot); zero_acc256(acc); }
;     ...
;     G_WAIT_V(6); G_BAR; G_MMA(1, 1, At, B1); G_BAR;
;     if (MODE && ((tt + 1) & 3) == 3) br_flush(p, acc, (tt + 1) >> 2);
;   }
;   {
;     G_LDB(B0, 0, 0); G_LDA(At, 0, 0); G_STAGE(G_SA(1, 1), A, oa0, oa1, LDA, 128, KA(nt - 1));
; DI void gate_reg(PREF p, int l, int n, f32x4 (&acc)[2][2][4][2], int dt) {
;     ...
;   const float* bm = p.b_merge + (size_t)l * 4096 + n * 1024 + dt * 256 + wc * 32 + fr;
;   float bias[2][2];
; #pragma unroll
;   for (int bj = 0; bj < 2; ++bj)
; #pragma unroll
;     for (int nn = 0; nn < 2; ++nn) bias[bj][nn] = bm[bj * 128 + nn * 16];
; #pragma unroll
;   for (int ai = 0; ai < 2; ++ai)
; #pragma unroll
;     for (int bj = 0; bj < 2; ++bj) {
;       __builtin_amdgcn_sched_barrier(0);
;       u32x4 bn[4], pv[4];
; #pragma unroll
;       for (int m = 0; m < 4; ++m) {
;         bn[m] = sbn[((ai * 2 + bj) * 4 + m) * 64];
;         if (n > 0) pv[m] = ssum[((ai * 2 + bj) * 4 + m) * 64];
	s_waitcnt lgkmcnt(0)
	s_setprio 1
	s_waitcnt lgkmcnt(0)
	v_mfma_f32_16x16x32_bf16 v[62:65], v[194:197], v[164:167], v[62:65]
	v_mfma_f32_16x16x32_bf16 v[58:61], v[194:197], v[186:189], v[58:61]
	v_mfma_f32_16x16x32_bf16 v[54:57], v[202:205], v[164:167], v[54:57]
	v_mfma_f32_16x16x32_bf16 v[50:53], v[202:205], v[186:189], v[50:53]
	v_mfma_f32_16x16x32_bf16 v[46:49], v[210:213], v[164:167], v[46:49]
	v_mfma_f32_16x16x32_bf16 v[42:45], v[210:213], v[186:189], v[42:45]
	v_mfma_f32_16x16x32_bf16 v[38:41], v[218:221], v[164:167], v[38:41]
	v_mfma_f32_16x16x32_bf16 v[34:37], v[218:221], v[186:189], v[34:37]
	v_mfma_f32_16x16x32_bf16 v[62:65], v[198:201], v[182:185], v[62:65]
	v_mfma_f32_16x16x32_bf16 v[58:61], v[198:201], v[190:193], v[58:61]
	v_mfma_f32_16x16x32_bf16 v[54:57], v[206:209], v[182:185], v[54:57]
	v_mfma_f32_16x16x32_bf16 v[50:53], v[206:209], v[190:193], v[50:53]
	v_mfma_f32_16x16x32_bf16 v[46:49], v[214:217], v[182:185], v[46:49]
	v_mfma_f32_16x16x32_bf16 v[42:45], v[214:217], v[190:193], v[42:45]
	v_mfma_f32_16x16x32_bf16 v[38:41], v[222:225], v[182:185], v[38:41]
	v_mfma_f32_16x16x32_bf16 v[34:37], v[222:225], v[190:193], v[34:37]
	s_setprio 0
	s_barrier
	v_readfirstlane_b32 s0, v157
	v_lshl_add_u64 v[164:165], v[246:247], 0, s[74:75]
	s_mov_b32 m0, s0
	v_readfirstlane_b32 s0, v159
	global_load_lds_dwordx4 v[164:165], off
	v_lshl_add_u64 v[164:165], v[248:249], 0, s[74:75]
	s_mov_b32 m0, s0
	s_nop 0
	global_load_lds_dwordx4 v[164:165], off
	s_waitcnt vmcnt(6)
	s_barrier
	s_setprio 1
	v_mfma_f32_16x16x32_bf16 v[30:33], v[194:197], v[226:229], v[30:33]
	v_mfma_f32_16x16x32_bf16 v[26:29], v[194:197], v[234:237], v[26:29]
	v_mfma_f32_16x16x32_bf16 v[22:25], v[202:205], v[226:229], v[22:25]
	v_mfma_f32_16x16x32_bf16 v[18:21], v[202:205], v[234:237], v[18:21]
	v_mfma_f32_16x16x32_bf16 v[14:17], v[210:213], v[226:229], v[14:17]
	v_mfma_f32_16x16x32_bf16 v[10:13], v[210:213], v[234:237], v[10:13]
	v_mfma_f32_16x16x32_bf16 v[6:9], v[218:221], v[226:229], v[6:9]
	v_mfma_f32_16x16x32_bf16 v[2:5], v[218:221], v[234:237], v[2:5]
	v_mfma_f32_16x16x32_bf16 v[30:33], v[198:201], v[230:233], v[30:33]
	v_mfma_f32_16x16x32_bf16 v[26:29], v[198:201], v[238:241], v[26:29]
	v_mfma_f32_16x16x32_bf16 v[22:25], v[206:209], v[230:233], v[22:25]
	v_mfma_f32_16x16x32_bf16 v[18:21], v[206:209], v[238:241], v[18:21]
	v_mfma_f32_16x16x32_bf16 v[14:17], v[214:217], v[230:233], v[14:17]
	v_mfma_f32_16x16x32_bf16 v[10:13], v[214:217], v[238:241], v[10:13]
	v_mfma_f32_16x16x32_bf16 v[6:9], v[222:225], v[230:233], v[6:9]
	v_mfma_f32_16x16x32_bf16 v[2:5], v[222:225], v[238:241], v[2:5]
	s_setprio 0
	s_add_i32 s10, s10, 2
	s_add_u32 s8, s8, 0x100
	s_addc_u32 s9, s9, 0
	s_cmp_lt_u32 s10, 12
	s_barrier
	s_cbranch_scc1 .LBB0_105
	v_readfirstlane_b32 s0, v161
	v_lshl_add_u64 v[132:133], v[132:133], 1, s[34:35]
	s_mov_b32 m0, s0
	v_readfirstlane_b32 s0, v162
	ds_read_b128 v[134:137], v160
	ds_read_b128 v[138:141], v160 offset:1024
	ds_read_b128 v[150:153], v160 offset:2048
	ds_read_b128 v[154:157], v160 offset:3072
	ds_read_b128 v[164:167], v142
	ds_read_b128 v[182:185], v142 offset:1024
	ds_read_b128 v[186:189], v142 offset:2048
	ds_read_b128 v[190:193], v142 offset:3072
	ds_read_b128 v[194:197], v142 offset:4096
	ds_read_b128 v[198:201], v142 offset:5120
	ds_read_b128 v[202:205], v142 offset:6144
	ds_read_b128 v[206:209], v142 offset:7168
	global_load_lds_dwordx4 v[132:133], off
	v_lshl_add_u64 v[130:131], v[130:131], 1, s[34:35]
	s_mov_b32 m0, s0
	s_nop 0
	global_load_lds_dwordx4 v[130:131], off
	s_lshl_b32 s1, s23, 8
	s_add_u32 s98, s25, s1
	s_addc_u32 s99, s48, 0
	v_bfe_u32 v251, v168, 6, 2
	v_lshlrev_b32_e32 v248, 6, v251
	v_and_b32_e32 v250, 15, v168
	v_lshl_or_b32 v248, v250, 2, v248
	global_load_dword v170, v248, s[98:99]
	s_add_u32 s98, s98, 0x1000
	s_addc_u32 s99, s99, 0
	global_load_dword v252, v248, s[98:99]
	s_add_u32 s98, s98, 0x1000
	s_addc_u32 s99, s99, 0
	global_load_dword v253, v248, s[98:99]
	s_add_u32 s98, s98, 0x1000
	s_addc_u32 s99, s99, 0
	global_load_dword v162, v248, s[98:99]
	s_lshl_b32 s1, s23, 1
	v_lshrrev_b32_e32 v249, 1, v251
	v_add_u32_e32 v249, s1, v249
	v_and_b32_e32 v249, 3, v249
	v_lshrrev_b32_e32 v250, 8, v168
	v_lshl_add_u32 v249, v250, 2, v249
	v_lshlrev_b32_e32 v249, 14, v249
	v_and_b32_e32 v250, 63, v168
	v_lshl_or_b32 v249, v250, 4, v249
	v_and_b32_e32 v250, 1, v251
	v_lshl_or_b32 v249, v250, 3, v249
	s_lshr_b32 s1, s23, 1
	s_lshl_b32 s1, s1, 12
	s_add_u32 s20, s63, s1
	s_addc_u32 s21, s64, 0
	global_load_dwordx2 v[230:231], v249, s[20:21] offset:0
	global_load_dwordx2 v[238:239], v249, s[20:21] offset:1024
	s_add_u32 s20, s20, 0x20000
	s_addc_u32 s21, s21, 0
	global_load_dwordx2 v[232:233], v249, s[20:21] offset:0
	global_load_dwordx2 v[240:241], v249, s[20:21] offset:1024
	s_add_u32 s20, s20, 0x20000
	s_addc_u32 s21, s21, 0
	global_load_dwordx2 v[234:235], v249, s[20:21] offset:0
	global_load_dwordx2 v[242:243], v249, s[20:21] offset:1024
	s_add_u32 s20, s20, 0x20000
	s_addc_u32 s21, s21, 0
	global_load_dwordx2 v[236:237], v249, s[20:21] offset:0
	global_load_dwordx2 v[244:245], v249, s[20:21] offset:1024
	s_barrier
; #define G_LDA(dst, b, h)                                                                                                  \
;   _Pragma("unroll") for (int m = 0; m < 4; ++m) _Pragma("unroll") for (int k = 0; k < 2; ++k)                             \
;       dst[m][k] = *(const bf16x8*)((const char*)G_SA(b, h) + ((wr * 4 + m) * 2 + k) * 1024 + rdo)
; #define G_LDB(dst, b, h)                                                                                                  \
;   _Pragma("unroll") for (int n = 0; n < 2; ++n) _Pragma("unroll") for (int k = 0; k < 2; ++k)                             \
;       dst[n][k] = *(const bf16x8*)((const char*)G_SB(b, h) + ((wc * 2 + n) * 2 + k) * 1024 + rdo)
; #define G_WAIT_V(n) asm volatile("s_waitcnt vmcnt(" #n ")" ::: "memory")
; #define G_WAIT_L(n) asm volatile("s_waitcnt lgkmcnt(" #n ")" ::: "memory")
; #define G_BAR __builtin_amdgcn_s_barrier()
;     ...
;     G_LDB(B0, 0, 0); G_LDA(At, 0, 0); G_STAGE(G_SA(1, 1), A, oa0, oa1, LDA, 128, KA(nt - 1));
;     G_BAR; G_WAIT_L(0); G_MMA(0, 0, At, B0); G_BAR;
;     G_LDB(B1, 0, 1); G_BAR; G_WAIT_L(0); G_MMA(0, 1, At, B1); G_BAR;
;     G_LDA(At, 0, 1); G_WAIT_V(4); G_BAR; G_WAIT_L(0); G_MMA(1, 0, At, B0); G_MMA(1, 1, At, B1); G_BAR;
;   }
	s_waitcnt lgkmcnt(0)
	s_setprio 1
	s_waitcnt lgkmcnt(0)
	v_mfma_f32_16x16x32_bf16 v[126:129], v[164:167], v[134:137], v[126:129]
	v_mfma_f32_16x16x32_bf16 v[122:125], v[164:167], v[150:153], v[122:125]
	v_mfma_f32_16x16x32_bf16 v[114:117], v[186:189], v[150:153], v[114:117]
	v_mfma_f32_16x16x32_bf16 v[110:113], v[194:197], v[134:137], v[110:113]
	v_mfma_f32_16x16x32_bf16 v[106:109], v[194:197], v[150:153], v[106:109]
	v_mfma_f32_16x16x32_bf16 v[102:105], v[202:205], v[134:137], v[102:105]
	v_mfma_f32_16x16x32_bf16 v[98:101], v[202:205], v[150:153], v[98:101]
	v_mfma_f32_16x16x32_bf16 v[126:129], v[182:185], v[138:141], v[126:129]
	v_mfma_f32_16x16x32_bf16 v[122:125], v[182:185], v[154:157], v[122:125]
	v_mfma_f32_16x16x32_bf16 v[118:121], v[186:189], v[134:137], v[118:121]
	v_mfma_f32_16x16x32_bf16 v[114:117], v[190:193], v[154:157], v[114:117]
	v_mfma_f32_16x16x32_bf16 v[110:113], v[198:201], v[138:141], v[110:113]
	v_mfma_f32_16x16x32_bf16 v[106:109], v[198:201], v[154:157], v[106:109]
	v_mfma_f32_16x16x32_bf16 v[102:105], v[206:209], v[138:141], v[102:105]
	v_mfma_f32_16x16x32_bf16 v[98:101], v[206:209], v[154:157], v[98:101]
	v_mfma_f32_16x16x32_bf16 v[118:121], v[190:193], v[138:141], v[118:121]
	s_setprio 0
	s_barrier
	ds_read_b128 v[130:133], v158
	ds_read_b128 v[210:213], v158 offset:1024
	ds_read_b128 v[214:217], v158 offset:2048
	ds_read_b128 v[158:161], v158 offset:3072
	s_barrier
	s_waitcnt lgkmcnt(0)
	s_setprio 1
	s_waitcnt lgkmcnt(0)
	v_mfma_f32_16x16x32_bf16 v[94:97], v[164:167], v[130:133], v[94:97]
	v_mfma_f32_16x16x32_bf16 v[90:93], v[164:167], v[214:217], v[90:93]
	v_mfma_f32_16x16x32_bf16 v[86:89], v[186:189], v[130:133], v[86:89]
	v_mfma_f32_16x16x32_bf16 v[82:85], v[186:189], v[214:217], v[82:85]
	v_mfma_f32_16x16x32_bf16 v[78:81], v[194:197], v[130:133], v[78:81]
	v_mfma_f32_16x16x32_bf16 v[74:77], v[194:197], v[214:217], v[74:77]
	v_mfma_f32_16x16x32_bf16 v[70:73], v[202:205], v[130:133], v[70:73]
	v_mfma_f32_16x16x32_bf16 v[66:69], v[202:205], v[214:217], v[66:69]
	v_mfma_f32_16x16x32_bf16 v[94:97], v[182:185], v[210:213], v[94:97]
	v_mfma_f32_16x16x32_bf16 v[90:93], v[182:185], v[158:161], v[90:93]
	v_mfma_f32_16x16x32_bf16 v[86:89], v[190:193], v[210:213], v[86:89]
	v_mfma_f32_16x16x32_bf16 v[82:85], v[190:193], v[158:161], v[82:85]
	v_mfma_f32_16x16x32_bf16 v[78:81], v[198:201], v[210:213], v[78:81]
	v_mfma_f32_16x16x32_bf16 v[74:77], v[198:201], v[158:161], v[74:77]
	v_mfma_f32_16x16x32_bf16 v[70:73], v[206:209], v[210:213], v[70:73]
	v_mfma_f32_16x16x32_bf16 v[66:69], v[206:209], v[158:161], v[66:69]
	s_setprio 0
	s_barrier
	ds_read_b128 v[164:167], v142 offset:16384
	ds_read_b128 v[182:185], v142 offset:17408
	ds_read_b128 v[186:189], v142 offset:18432
	ds_read_b128 v[190:193], v142 offset:19456
	ds_read_b128 v[194:197], v142 offset:20480
	ds_read_b128 v[198:201], v142 offset:21504
	ds_read_b128 v[202:205], v142 offset:22528
	ds_read_b128 v[206:209], v142 offset:23552
	s_waitcnt vmcnt(16)
	s_barrier
	s_waitcnt lgkmcnt(0)
	s_setprio 1
	s_waitcnt lgkmcnt(0)
	v_mfma_f32_16x16x32_bf16 v[62:65], v[164:167], v[134:137], v[62:65]
	v_mfma_f32_16x16x32_bf16 v[58:61], v[164:167], v[150:153], v[58:61]
	v_mfma_f32_16x16x32_bf16 v[54:57], v[186:189], v[134:137], v[54:57]
	v_mfma_f32_16x16x32_bf16 v[50:53], v[186:189], v[150:153], v[50:53]
	v_mfma_f32_16x16x32_bf16 v[46:49], v[194:197], v[134:137], v[46:49]
	v_mfma_f32_16x16x32_bf16 v[38:41], v[202:205], v[134:137], v[38:41]
	v_mfma_f32_16x16x32_bf16 v[34:37], v[202:205], v[150:153], v[34:37]
	v_mfma_f32_16x16x32_bf16 v[62:65], v[182:185], v[138:141], v[62:65]
	v_mfma_f32_16x16x32_bf16 v[58:61], v[182:185], v[154:157], v[58:61]
	v_mfma_f32_16x16x32_bf16 v[54:57], v[190:193], v[138:141], v[54:57]
	v_mfma_f32_16x16x32_bf16 v[50:53], v[190:193], v[154:157], v[50:53]
	v_mfma_f32_16x16x32_bf16 v[46:49], v[198:201], v[138:141], v[46:49]
	v_mfma_f32_16x16x32_bf16 v[42:45], v[194:197], v[150:153], v[42:45]
	v_mfma_f32_16x16x32_bf16 v[38:41], v[206:209], v[138:141], v[38:41]
	v_mfma_f32_16x16x32_bf16 v[34:37], v[206:209], v[154:157], v[34:37]
	v_mfma_f32_16x16x32_bf16 v[42:45], v[198:201], v[154:157], v[42:45]
	s_setprio 0
	s_setprio 1
	v_mfma_f32_16x16x32_bf16 v[26:29], v[164:167], v[214:217], v[26:29]
	v_mfma_f32_16x16x32_bf16 v[22:25], v[186:189], v[130:133], v[22:25]
	v_mfma_f32_16x16x32_bf16 v[14:17], v[194:197], v[130:133], v[14:17]
	v_mfma_f32_16x16x32_bf16 v[10:13], v[194:197], v[214:217], v[10:13]
	v_mfma_f32_16x16x32_bf16 v[2:5], v[202:205], v[214:217], v[2:5]
	v_mfma_f32_16x16x32_bf16 v[30:33], v[164:167], v[130:133], v[30:33]
	v_mfma_f32_16x16x32_bf16 v[26:29], v[182:185], v[158:161], v[26:29]
	v_mfma_f32_16x16x32_bf16 v[22:25], v[190:193], v[210:213], v[22:25]
	v_mfma_f32_16x16x32_bf16 v[18:21], v[186:189], v[214:217], v[18:21]
	v_mfma_f32_16x16x32_bf16 v[14:17], v[198:201], v[210:213], v[14:17]
	v_mfma_f32_16x16x32_bf16 v[10:13], v[198:201], v[158:161], v[10:13]
	v_mfma_f32_16x16x32_bf16 v[6:9], v[202:205], v[130:133], v[6:9]
	v_mfma_f32_16x16x32_bf16 v[2:5], v[206:209], v[158:161], v[2:5]
	v_mfma_f32_16x16x32_bf16 v[30:33], v[182:185], v[210:213], v[30:33]
	v_mfma_f32_16x16x32_bf16 v[18:21], v[190:193], v[158:161], v[18:21]
	v_mfma_f32_16x16x32_bf16 v[6:9], v[206:209], v[210:213], v[6:9]
	s_setprio 0
	s_barrier
	ds_read_b128 v[130:133], v148
	ds_read_b128 v[154:157], v148 offset:1024
	ds_read_b128 v[164:167], v148 offset:2048
	ds_read_b128 v[182:185], v148 offset:3072
	ds_read_b128 v[186:189], v142 offset:32768
	ds_read_b128 v[190:193], v142 offset:33792
	ds_read_b128 v[194:197], v142 offset:34816
	ds_read_b128 v[198:201], v142 offset:35840
	ds_read_b128 v[202:205], v142 offset:36864
	ds_read_b128 v[206:209], v142 offset:37888
	ds_read_b128 v[210:213], v142 offset:38912
	ds_read_b128 v[214:217], v142 offset:39936
	s_waitcnt vmcnt(14)
	s_barrier
; #define G_LDA(dst, b, h)                                                                                                  \
;   _Pragma("unroll") for (int m = 0; m < 4; ++m) _Pragma("unroll") for (int k = 0; k < 2; ++k)                             \
;       dst[m][k] = *(const bf16x8*)((const char*)G_SA(b, h) + ((wr * 4 + m) * 2 + k) * 1024 + rdo)
; #define G_LDB(dst, b, h)                                                                                                  \
;   _Pragma("unroll") for (int n = 0; n < 2; ++n) _Pragma("unroll") for (int k = 0; k < 2; ++k)                             \
;       dst[n][k] = *(const bf16x8*)((const char*)G_SB(b, h) + ((wc * 2 + n) * 2 + k) * 1024 + rdo)
; #define G_WAIT_V(n) asm volatile("s_waitcnt vmcnt(" #n ")" ::: "memory")
; #define G_WAIT_L(n) asm volatile("s_waitcnt lgkmcnt(" #n ")" ::: "memory")
; #define G_BAR __builtin_amdgcn_s_barrier()
;     ...
;   {
;     G_LDB(B0, 1, 0); G_LDA(At, 1, 0); G_WAIT_V(2); G_BAR; G_WAIT_L(0); G_MMA(0, 0, At, B0); G_BAR;
;     G_LDB(B1, 1, 1); G_WAIT_V(0); G_BAR; G_WAIT_L(0); G_MMA(0, 1, At, B1); G_BAR;
;     G_LDA(At, 1, 1); G_BAR; G_WAIT_L(0); G_MMA(1, 0, At, B0); G_MMA(1, 1, At, B1); G_BAR;
;   }
;   if (wr == 0) G_BAR;
	s_waitcnt lgkmcnt(0)
	s_setprio 1
	s_waitcnt lgkmcnt(0)
	v_mfma_f32_16x16x32_bf16 v[126:129], v[186:189], v[130:133], v[126:129]
	v_mfma_f32_16x16x32_bf16 v[122:125], v[186:189], v[164:167], v[122:125]
	v_mfma_f32_16x16x32_bf16 v[118:121], v[194:197], v[130:133], v[118:121]
	v_mfma_f32_16x16x32_bf16 v[114:117], v[194:197], v[164:167], v[114:117]
	v_mfma_f32_16x16x32_bf16 v[110:113], v[202:205], v[130:133], v[110:113]
	v_mfma_f32_16x16x32_bf16 v[106:109], v[202:205], v[164:167], v[106:109]
	v_mfma_f32_16x16x32_bf16 v[102:105], v[210:213], v[130:133], v[102:105]
	v_mfma_f32_16x16x32_bf16 v[98:101], v[210:213], v[164:167], v[98:101]
	v_mfma_f32_16x16x32_bf16 v[158:161], v[190:193], v[154:157], v[126:129]
	v_mfma_f32_16x16x32_bf16 v[150:153], v[190:193], v[182:185], v[122:125]
	v_mfma_f32_16x16x32_bf16 v[146:149], v[198:201], v[154:157], v[118:121]
	v_mfma_f32_16x16x32_bf16 v[138:141], v[198:201], v[182:185], v[114:117]
	v_mfma_f32_16x16x32_bf16 v[134:137], v[206:209], v[154:157], v[110:113]
	v_mfma_f32_16x16x32_bf16 v[126:129], v[206:209], v[182:185], v[106:109]
	v_mfma_f32_16x16x32_bf16 v[122:125], v[214:217], v[154:157], v[102:105]
	v_mfma_f32_16x16x32_bf16 v[114:117], v[214:217], v[182:185], v[98:101]
	s_setprio 0
	s_barrier
	ds_read_b128 v[118:121], v145
	ds_read_b128 v[218:221], v145 offset:1024
	ds_read_b128 v[222:225], v145 offset:2048
	ds_read_b128 v[226:229], v145 offset:3072
	s_waitcnt vmcnt(12)
	s_barrier
	s_waitcnt lgkmcnt(0)
	s_setprio 1
	s_waitcnt lgkmcnt(0)
	v_mfma_f32_16x16x32_bf16 v[94:97], v[186:189], v[118:121], v[94:97]
	v_mfma_f32_16x16x32_bf16 v[90:93], v[186:189], v[222:225], v[90:93]
	v_mfma_f32_16x16x32_bf16 v[86:89], v[194:197], v[118:121], v[86:89]
	v_mfma_f32_16x16x32_bf16 v[82:85], v[194:197], v[222:225], v[82:85]
	v_mfma_f32_16x16x32_bf16 v[78:81], v[202:205], v[118:121], v[78:81]
	v_mfma_f32_16x16x32_bf16 v[74:77], v[202:205], v[222:225], v[74:77]
	v_mfma_f32_16x16x32_bf16 v[70:73], v[210:213], v[118:121], v[70:73]
	v_mfma_f32_16x16x32_bf16 v[66:69], v[210:213], v[222:225], v[66:69]
	v_mfma_f32_16x16x32_bf16 v[110:113], v[190:193], v[218:221], v[94:97]
	v_mfma_f32_16x16x32_bf16 v[106:109], v[190:193], v[226:229], v[90:93]
	v_mfma_f32_16x16x32_bf16 v[102:105], v[198:201], v[218:221], v[86:89]
	v_mfma_f32_16x16x32_bf16 v[98:101], v[198:201], v[226:229], v[82:85]
	v_mfma_f32_16x16x32_bf16 v[94:97], v[206:209], v[218:221], v[78:81]
	v_mfma_f32_16x16x32_bf16 v[90:93], v[206:209], v[226:229], v[74:77]
	v_mfma_f32_16x16x32_bf16 v[86:89], v[214:217], v[218:221], v[70:73]
	v_mfma_f32_16x16x32_bf16 v[82:85], v[214:217], v[226:229], v[66:69]
	s_setprio 0
	s_barrier
	ds_read_b128 v[186:189], v142 offset:49152
	ds_read_b128 v[190:193], v142 offset:50176
	ds_read_b128 v[194:197], v142 offset:51200
	ds_read_b128 v[198:201], v142 offset:52224
	ds_read_b128 v[202:205], v142 offset:53248
	ds_read_b128 v[206:209], v142 offset:54272
	ds_read_b128 v[210:213], v142 offset:55296
	ds_read_b128 v[142:145], v142 offset:56320
	s_barrier
	s_waitcnt lgkmcnt(0)
	s_setprio 1
	s_waitcnt lgkmcnt(0)
	v_mfma_f32_16x16x32_bf16 v[62:65], v[186:189], v[130:133], v[62:65]
	v_mfma_f32_16x16x32_bf16 v[58:61], v[186:189], v[164:167], v[58:61]
	v_mfma_f32_16x16x32_bf16 v[54:57], v[194:197], v[130:133], v[54:57]
	v_mfma_f32_16x16x32_bf16 v[50:53], v[194:197], v[164:167], v[50:53]
	v_mfma_f32_16x16x32_bf16 v[46:49], v[202:205], v[130:133], v[46:49]
	v_mfma_f32_16x16x32_bf16 v[42:45], v[202:205], v[164:167], v[42:45]
	v_mfma_f32_16x16x32_bf16 v[38:41], v[210:213], v[130:133], v[38:41]
	v_mfma_f32_16x16x32_bf16 v[34:37], v[210:213], v[164:167], v[34:37]
	v_mfma_f32_16x16x32_bf16 v[78:81], v[190:193], v[154:157], v[62:65]
	v_mfma_f32_16x16x32_bf16 v[74:77], v[190:193], v[182:185], v[58:61]
	v_mfma_f32_16x16x32_bf16 v[70:73], v[198:201], v[154:157], v[54:57]
	v_mfma_f32_16x16x32_bf16 v[66:69], v[198:201], v[182:185], v[50:53]
	v_mfma_f32_16x16x32_bf16 v[62:65], v[206:209], v[154:157], v[46:49]
	v_mfma_f32_16x16x32_bf16 v[58:61], v[206:209], v[182:185], v[42:45]
	v_mfma_f32_16x16x32_bf16 v[54:57], v[142:145], v[154:157], v[38:41]
	v_mfma_f32_16x16x32_bf16 v[50:53], v[142:145], v[182:185], v[34:37]
	s_setprio 0
	s_setprio 1
	v_mfma_f32_16x16x32_bf16 v[30:33], v[186:189], v[118:121], v[30:33]
	v_mfma_f32_16x16x32_bf16 v[26:29], v[186:189], v[222:225], v[26:29]
	v_mfma_f32_16x16x32_bf16 v[22:25], v[194:197], v[118:121], v[22:25]
	v_mfma_f32_16x16x32_bf16 v[18:21], v[194:197], v[222:225], v[18:21]
	v_mfma_f32_16x16x32_bf16 v[14:17], v[202:205], v[118:121], v[14:17]
	v_mfma_f32_16x16x32_bf16 v[10:13], v[202:205], v[222:225], v[10:13]
	v_mfma_f32_16x16x32_bf16 v[6:9], v[210:213], v[118:121], v[6:9]
	v_mfma_f32_16x16x32_bf16 v[2:5], v[210:213], v[222:225], v[2:5]
	v_mfma_f32_16x16x32_bf16 v[46:49], v[190:193], v[218:221], v[30:33]
	v_mfma_f32_16x16x32_bf16 v[38:41], v[190:193], v[226:229], v[26:29]
	v_mfma_f32_16x16x32_bf16 v[34:37], v[198:201], v[218:221], v[22:25]
	v_mfma_f32_16x16x32_bf16 v[26:29], v[198:201], v[226:229], v[18:21]
	v_mfma_f32_16x16x32_bf16 v[22:25], v[206:209], v[218:221], v[14:17]
	v_mfma_f32_16x16x32_bf16 v[14:17], v[206:209], v[226:229], v[10:13]
	v_mfma_f32_16x16x32_bf16 v[10:13], v[142:145], v[218:221], v[6:9]
	v_mfma_f32_16x16x32_bf16 v[2:5], v[142:145], v[226:229], v[2:5]
	s_setprio 0
	v_cmp_gt_u32_e32 vcc, s67, v0
	s_barrier
	s_and_saveexec_b64 s[8:9], vcc
	s_cbranch_execz .LBB0_108
	s_barrier
; DI float sigm(float x) { return 1.f / (1.f + __expf(-x)); }
; DI void gate_reg(PREF p, int l, int n, f32x4 (&acc)[2][2][4][2], int dt) {
;     ...
;       u32x4 bn[4], pv[4];
; #pragma unroll
;       for (int m = 0; m < 4; ++m) {
;         bn[m] = sbn[((ai * 2 + bj) * 4 + m) * 64];
;         if (n > 0) pv[m] = ssum[((ai * 2 + bj) * 4 + m) * 64];
;       }
; #pragma unroll
;       for (int m = 0; m < 4; ++m) {
;         float b[8]; unpack8(bn[m], b);
;         float v[8];
; #pragma unroll
;         for (int nn = 0; nn < 2; ++nn)
; #pragma unroll
;           for (int j = 0; j < 4; ++j) v[nn * 4 + j] = sigm(acc[ai][bj][m][nn][j] + bias[bj][nn]) * b[nn * 4 + j];
;         if (n > 0) {
;           float o[8]; unpack8(pv[m], o);
; #pragma unroll
;           for (int e = 0; e < 8; ++e) v[e] += o[e];
.LBB0_108:
	s_or_b64 exec, exec, s[8:9]
	s_lshl_b32 s0, s23, 8
	s_add_u32 s98, s25, s0
	s_addc_u32 s99, s48, 0
	s_lshr_b32 s0, s23, 1
	s_lshl_b32 s0, s0, 12
	s_add_u32 s8, s63, s0
	s_addc_u32 s9, s64, 0
	s_add_u32 s10, s8, 0x20000
	s_addc_u32 s11, s9, 0
	s_add_u32 s42, s8, 0x40000
	s_addc_u32 s43, s9, 0
	s_add_u32 s44, s8, 0x60000
	s_addc_u32 s45, s9, 0
	s_lshl_b32 s0, s23, 1
	v_bfe_u32 v155, v168, 6, 2
	v_lshlrev_b32_e32 v130, 6, v155
	v_and_b32_e32 v131, 15, v168
	v_lshl_or_b32 v130, v131, 2, v130
	v_add_u32_e32 v131, 0x1000, v130
	v_add_u32_e32 v131, 0x2000, v130
	v_add_u32_e32 v131, 0x3000, v130
	v_lshrrev_b32_e32 v130, 1, v155
	v_add_u32_e32 v130, s0, v130
	v_and_b32_e32 v130, 3, v130
	v_lshrrev_b32_e32 v131, 8, v168
	v_lshl_add_u32 v130, v131, 2, v130
	v_lshlrev_b32_e32 v130, 14, v130
	v_and_b32_e32 v131, 63, v168
	v_lshl_or_b32 v142, v131, 4, v130
	v_and_b32_e32 v131, 1, v155
	v_lshl_or_b32 v142, v131, 3, v142
	v_add_u32_e32 v0, 0x2000, v142
	global_load_dwordx2 v[198:199], v142, s[8:9] offset:2048
	global_load_dwordx2 v[200:201], v142, s[10:11] offset:2048
	global_load_dwordx2 v[202:203], v142, s[42:43] offset:2048
	global_load_dwordx2 v[204:205], v142, s[44:45] offset:2048
	global_load_dwordx2 v[206:207], v142, s[8:9] offset:3072
	global_load_dwordx2 v[208:209], v142, s[10:11] offset:3072
	global_load_dwordx2 v[210:211], v142, s[42:43] offset:3072
	global_load_dwordx2 v[212:213], v142, s[44:45] offset:3072
	global_load_dwordx2 v[214:215], v0, s[8:9] offset:0
	global_load_dwordx2 v[216:217], v0, s[10:11] offset:0
	global_load_dwordx2 v[218:219], v0, s[42:43] offset:0
	global_load_dwordx2 v[220:221], v0, s[44:45] offset:0
	global_load_dwordx2 v[222:223], v0, s[8:9] offset:1024
	global_load_dwordx2 v[224:225], v0, s[10:11] offset:1024
	global_load_dwordx2 v[226:227], v0, s[42:43] offset:1024
	global_load_dwordx2 v[228:229], v0, s[44:45] offset:1024
	global_load_dwordx2 v[182:183], v0, s[8:9] offset:2048
	global_load_dwordx2 v[184:185], v0, s[10:11] offset:2048
	global_load_dwordx2 v[186:187], v0, s[42:43] offset:2048
	global_load_dwordx2 v[188:189], v0, s[44:45] offset:2048
	global_load_dwordx2 v[190:191], v0, s[8:9] offset:3072
	global_load_dwordx2 v[192:193], v0, s[10:11] offset:3072
	global_load_dwordx2 v[194:195], v0, s[42:43] offset:3072
	global_load_dwordx2 v[196:197], v0, s[44:45] offset:3072
	s_waitcnt vmcnt(24)
	v_add_f32_e32 v158, v158, v170
	v_mul_f32_e32 v158, 0xbfb8aa3b, v158
	v_exp_f32_e32 v158, v158
	v_add_f32_e32 v159, v159, v170
	v_mul_f32_e32 v159, 0xbfb8aa3b, v159
	v_exp_f32_e32 v159, v159
	v_add_f32_e32 v160, v160, v170
	v_mul_f32_e32 v160, 0xbfb8aa3b, v160
	v_exp_f32_e32 v160, v160
	v_add_f32_e32 v161, v161, v170
	v_mul_f32_e32 v161, 0xbfb8aa3b, v161
	v_exp_f32_e32 v161, v161
	v_add_f32_e32 v150, v150, v252
	v_mul_f32_e32 v150, 0xbfb8aa3b, v150
	v_exp_f32_e32 v150, v150
	v_add_f32_e32 v151, v151, v252
	v_mul_f32_e32 v151, 0xbfb8aa3b, v151
	v_exp_f32_e32 v151, v151
	v_add_f32_e32 v152, v152, v252
	v_mul_f32_e32 v152, 0xbfb8aa3b, v152
	v_exp_f32_e32 v152, v152
	v_add_f32_e32 v153, v153, v252
	v_mul_f32_e32 v153, 0xbfb8aa3b, v153
	v_exp_f32_e32 v153, v153
	v_add_f32_e32 v110, v110, v253
	v_mul_f32_e32 v110, 0xbfb8aa3b, v110
	v_exp_f32_e32 v110, v110
	v_add_f32_e32 v111, v111, v253
	v_mul_f32_e32 v111, 0xbfb8aa3b, v111
	v_exp_f32_e32 v111, v111
	v_add_f32_e32 v112, v112, v253
	v_mul_f32_e32 v112, 0xbfb8aa3b, v112
	v_exp_f32_e32 v112, v112
	v_add_f32_e32 v113, v113, v253
	v_mul_f32_e32 v113, 0xbfb8aa3b, v113
	v_exp_f32_e32 v113, v113
	v_add_f32_e32 v106, v106, v162
	v_mul_f32_e32 v106, 0xbfb8aa3b, v106
	v_exp_f32_e32 v106, v106
	v_add_f32_e32 v107, v107, v162
	v_mul_f32_e32 v107, 0xbfb8aa3b, v107
	v_exp_f32_e32 v107, v107
	v_add_f32_e32 v108, v108, v162
	v_mul_f32_e32 v108, 0xbfb8aa3b, v108
	v_exp_f32_e32 v108, v108
	v_add_f32_e32 v109, v109, v162
	v_mul_f32_e32 v109, 0xbfb8aa3b, v109
	v_exp_f32_e32 v109, v109
	v_pk_add_f32 v[158:159], v[158:159], 1.0 op_sel_hi:[1,0]
	v_lshlrev_b32_e32 v156, 16, v230
	v_and_b32_e32 v157, 0xffff0000, v230
	v_rcp_f32_e32 v158, v158
	v_rcp_f32_e32 v159, v159
	v_pk_add_f32 v[160:161], v[160:161], 1.0 op_sel_hi:[1,0]
	v_lshlrev_b32_e32 v164, 16, v231
	v_and_b32_e32 v165, 0xffff0000, v231
	v_rcp_f32_e32 v160, v160
	v_rcp_f32_e32 v161, v161
	v_pk_mul_f32 v[158:159], v[158:159], v[156:157]
	v_pk_mul_f32 v[160:161], v[160:161], v[164:165]
	v_pk_add_f32 v[150:151], v[150:151], 1.0 op_sel_hi:[1,0]
	v_lshlrev_b32_e32 v156, 16, v232
	v_and_b32_e32 v157, 0xffff0000, v232
	v_rcp_f32_e32 v150, v150
	v_rcp_f32_e32 v151, v151
	v_pk_add_f32 v[152:153], v[152:153], 1.0 op_sel_hi:[1,0]
	v_lshlrev_b32_e32 v164, 16, v233
	v_and_b32_e32 v165, 0xffff0000, v233
	v_rcp_f32_e32 v152, v152
	v_rcp_f32_e32 v153, v153
	v_pk_fma_f32 v[158:159], v[150:151], v[156:157], v[158:159]
	v_pk_fma_f32 v[160:161], v[152:153], v[164:165], v[160:161]
	v_pk_add_f32 v[110:111], v[110:111], 1.0 op_sel_hi:[1,0]
	v_lshlrev_b32_e32 v156, 16, v234
	v_and_b32_e32 v157, 0xffff0000, v234
	v_rcp_f32_e32 v110, v110
	v_rcp_f32_e32 v111, v111
	v_pk_add_f32 v[112:113], v[112:113], 1.0 op_sel_hi:[1,0]
	v_lshlrev_b32_e32 v164, 16, v235
	v_and_b32_e32 v165, 0xffff0000, v235
	v_rcp_f32_e32 v112, v112
	v_rcp_f32_e32 v113, v113
	v_pk_fma_f32 v[158:159], v[110:111], v[156:157], v[158:159]
	v_pk_fma_f32 v[160:161], v[112:113], v[164:165], v[160:161]
	v_pk_add_f32 v[106:107], v[106:107], 1.0 op_sel_hi:[1,0]
	v_lshlrev_b32_e32 v156, 16, v236
	v_and_b32_e32 v157, 0xffff0000, v236
	v_rcp_f32_e32 v106, v106
	v_rcp_f32_e32 v107, v107
	v_pk_add_f32 v[108:109], v[108:109], 1.0 op_sel_hi:[1,0]
	v_lshlrev_b32_e32 v164, 16, v237
	v_and_b32_e32 v165, 0xffff0000, v237
	v_rcp_f32_e32 v108, v108
	v_rcp_f32_e32 v109, v109
	v_pk_fma_f32 v[158:159], v[106:107], v[156:157], v[158:159]
	v_pk_fma_f32 v[160:161], v[108:109], v[164:165], v[160:161]
	s_waitcnt vmcnt(24)
; DI float sigm(float x) { return 1.f / (1.f + __expf(-x)); }
; DI void gate_reg(PREF p, int l, int n, f32x4 (&acc)[2][2][4][2], int dt) {
;     ...
; #pragma unroll
;       for (int m = 0; m < 4; ++m) {
;         float b[8]; unpack8(bn[m], b);
;         float v[8];
; #pragma unroll
;         for (int nn = 0; nn < 2; ++nn)
; #pragma unroll
;           for (int j = 0; j < 4; ++j) v[nn * 4 + j] = sigm(acc[ai][bj][m][nn][j] + bias[bj][nn]) * b[nn * 4 + j];
;         if (n > 0) {
;           float o[8]; unpack8(pv[m], o);
; #pragma unroll
;           for (int e = 0; e < 8; ++e) v[e] += o[e];
	v_add_f32_e32 v146, v146, v170
	v_mul_f32_e32 v146, 0xbfb8aa3b, v146
	v_exp_f32_e32 v146, v146
	v_add_f32_e32 v147, v147, v170
	v_mul_f32_e32 v147, 0xbfb8aa3b, v147
	v_exp_f32_e32 v147, v147
	v_add_f32_e32 v148, v148, v170
	v_mul_f32_e32 v148, 0xbfb8aa3b, v148
	v_exp_f32_e32 v148, v148
	v_add_f32_e32 v149, v149, v170
	v_mul_f32_e32 v149, 0xbfb8aa3b, v149
	v_exp_f32_e32 v149, v149
	v_add_f32_e32 v138, v138, v252
	v_mul_f32_e32 v138, 0xbfb8aa3b, v138
	v_exp_f32_e32 v138, v138
	v_add_f32_e32 v139, v139, v252
	v_mul_f32_e32 v139, 0xbfb8aa3b, v139
	v_exp_f32_e32 v139, v139
	v_add_f32_e32 v140, v140, v252
	v_mul_f32_e32 v140, 0xbfb8aa3b, v140
	v_exp_f32_e32 v140, v140
	v_add_f32_e32 v141, v141, v252
	v_mul_f32_e32 v141, 0xbfb8aa3b, v141
	v_exp_f32_e32 v141, v141
	v_add_f32_e32 v102, v102, v253
	v_mul_f32_e32 v102, 0xbfb8aa3b, v102
	v_exp_f32_e32 v102, v102
	v_add_f32_e32 v103, v103, v253
	v_mul_f32_e32 v103, 0xbfb8aa3b, v103
	v_exp_f32_e32 v103, v103
	v_add_f32_e32 v104, v104, v253
	v_mul_f32_e32 v104, 0xbfb8aa3b, v104
	v_exp_f32_e32 v104, v104
	v_add_f32_e32 v105, v105, v253
	v_mul_f32_e32 v105, 0xbfb8aa3b, v105
	v_exp_f32_e32 v105, v105
	v_add_f32_e32 v98, v98, v162
	v_mul_f32_e32 v98, 0xbfb8aa3b, v98
	v_exp_f32_e32 v98, v98
	v_add_f32_e32 v99, v99, v162
	v_mul_f32_e32 v99, 0xbfb8aa3b, v99
	v_exp_f32_e32 v99, v99
	v_add_f32_e32 v100, v100, v162
	v_mul_f32_e32 v100, 0xbfb8aa3b, v100
	v_exp_f32_e32 v100, v100
	v_add_f32_e32 v101, v101, v162
	v_mul_f32_e32 v101, 0xbfb8aa3b, v101
	v_exp_f32_e32 v101, v101
	v_pk_add_f32 v[146:147], v[146:147], 1.0 op_sel_hi:[1,0]
	v_lshlrev_b32_e32 v156, 16, v238
	v_and_b32_e32 v157, 0xffff0000, v238
	v_rcp_f32_e32 v146, v146
	v_rcp_f32_e32 v147, v147
	v_pk_add_f32 v[148:149], v[148:149], 1.0 op_sel_hi:[1,0]
	v_lshlrev_b32_e32 v164, 16, v239
	v_and_b32_e32 v165, 0xffff0000, v239
	v_rcp_f32_e32 v148, v148
	v_rcp_f32_e32 v149, v149
	v_pk_mul_f32 v[146:147], v[146:147], v[156:157]
	v_pk_mul_f32 v[148:149], v[148:149], v[164:165]
	v_pk_add_f32 v[138:139], v[138:139], 1.0 op_sel_hi:[1,0]
	v_lshlrev_b32_e32 v156, 16, v240
	v_and_b32_e32 v157, 0xffff0000, v240
	v_rcp_f32_e32 v138, v138
	v_rcp_f32_e32 v139, v139
	v_pk_add_f32 v[140:141], v[140:141], 1.0 op_sel_hi:[1,0]
	v_lshlrev_b32_e32 v164, 16, v241
	v_and_b32_e32 v165, 0xffff0000, v241
	v_rcp_f32_e32 v140, v140
	v_rcp_f32_e32 v141, v141
	v_pk_fma_f32 v[146:147], v[138:139], v[156:157], v[146:147]
	v_pk_fma_f32 v[148:149], v[140:141], v[164:165], v[148:149]
	v_pk_add_f32 v[102:103], v[102:103], 1.0 op_sel_hi:[1,0]
	v_lshlrev_b32_e32 v156, 16, v242
	v_and_b32_e32 v157, 0xffff0000, v242
	v_rcp_f32_e32 v102, v102
	v_rcp_f32_e32 v103, v103
	v_pk_add_f32 v[104:105], v[104:105], 1.0 op_sel_hi:[1,0]
	v_lshlrev_b32_e32 v164, 16, v243
	v_and_b32_e32 v165, 0xffff0000, v243
	v_rcp_f32_e32 v104, v104
	v_rcp_f32_e32 v105, v105
	v_pk_fma_f32 v[146:147], v[102:103], v[156:157], v[146:147]
	v_pk_fma_f32 v[148:149], v[104:105], v[164:165], v[148:149]
	v_pk_add_f32 v[98:99], v[98:99], 1.0 op_sel_hi:[1,0]
	v_lshlrev_b32_e32 v156, 16, v244
	v_and_b32_e32 v157, 0xffff0000, v244
	v_rcp_f32_e32 v98, v98
	v_rcp_f32_e32 v99, v99
	v_pk_add_f32 v[100:101], v[100:101], 1.0 op_sel_hi:[1,0]
	v_lshlrev_b32_e32 v164, 16, v245
	v_and_b32_e32 v165, 0xffff0000, v245
	v_rcp_f32_e32 v100, v100
	v_rcp_f32_e32 v101, v101
	v_pk_fma_f32 v[146:147], v[98:99], v[156:157], v[146:147]
	v_pk_fma_f32 v[148:149], v[100:101], v[164:165], v[148:149]
	s_waitcnt vmcnt(20)
	v_add_f32_e32 v134, v134, v170
	v_mul_f32_e32 v134, 0xbfb8aa3b, v134
	v_exp_f32_e32 v134, v134
	v_add_f32_e32 v135, v135, v170
	v_mul_f32_e32 v135, 0xbfb8aa3b, v135
	v_exp_f32_e32 v135, v135
	v_add_f32_e32 v136, v136, v170
	v_mul_f32_e32 v136, 0xbfb8aa3b, v136
	v_exp_f32_e32 v136, v136
	v_add_f32_e32 v137, v137, v170
	v_mul_f32_e32 v137, 0xbfb8aa3b, v137
	v_exp_f32_e32 v137, v137
	v_add_f32_e32 v126, v126, v252
	v_mul_f32_e32 v126, 0xbfb8aa3b, v126
	v_exp_f32_e32 v126, v126
	v_add_f32_e32 v127, v127, v252
	v_mul_f32_e32 v127, 0xbfb8aa3b, v127
	v_exp_f32_e32 v127, v127
	v_add_f32_e32 v128, v128, v252
	v_mul_f32_e32 v128, 0xbfb8aa3b, v128
	v_exp_f32_e32 v128, v128
	v_add_f32_e32 v129, v129, v252
	v_mul_f32_e32 v129, 0xbfb8aa3b, v129
	v_exp_f32_e32 v129, v129
	v_add_f32_e32 v94, v94, v253
	v_mul_f32_e32 v94, 0xbfb8aa3b, v94
	v_exp_f32_e32 v94, v94
	v_add_f32_e32 v95, v95, v253
	v_mul_f32_e32 v95, 0xbfb8aa3b, v95
	v_exp_f32_e32 v95, v95
	v_add_f32_e32 v96, v96, v253
	v_mul_f32_e32 v96, 0xbfb8aa3b, v96
	v_exp_f32_e32 v96, v96
	v_add_f32_e32 v97, v97, v253
	v_mul_f32_e32 v97, 0xbfb8aa3b, v97
	v_exp_f32_e32 v97, v97
	v_add_f32_e32 v90, v90, v162
	v_mul_f32_e32 v90, 0xbfb8aa3b, v90
	v_exp_f32_e32 v90, v90
	v_add_f32_e32 v91, v91, v162
	v_mul_f32_e32 v91, 0xbfb8aa3b, v91
	v_exp_f32_e32 v91, v91
	v_add_f32_e32 v92, v92, v162
	v_mul_f32_e32 v92, 0xbfb8aa3b, v92
	v_exp_f32_e32 v92, v92
	v_add_f32_e32 v93, v93, v162
	v_mul_f32_e32 v93, 0xbfb8aa3b, v93
	v_exp_f32_e32 v93, v93
	v_pk_add_f32 v[134:135], v[134:135], 1.0 op_sel_hi:[1,0]
	v_lshlrev_b32_e32 v156, 16, v198
	v_and_b32_e32 v157, 0xffff0000, v198
	v_rcp_f32_e32 v134, v134
	v_rcp_f32_e32 v135, v135
	v_pk_add_f32 v[136:137], v[136:137], 1.0 op_sel_hi:[1,0]
	v_lshlrev_b32_e32 v164, 16, v199
	v_and_b32_e32 v165, 0xffff0000, v199
	v_rcp_f32_e32 v136, v136
	v_rcp_f32_e32 v137, v137
	v_pk_mul_f32 v[134:135], v[134:135], v[156:157]
	v_pk_mul_f32 v[136:137], v[136:137], v[164:165]
	v_pk_add_f32 v[126:127], v[126:127], 1.0 op_sel_hi:[1,0]
	v_lshlrev_b32_e32 v156, 16, v200
	v_and_b32_e32 v157, 0xffff0000, v200
	v_rcp_f32_e32 v126, v126
	v_rcp_f32_e32 v127, v127
	v_pk_add_f32 v[128:129], v[128:129], 1.0 op_sel_hi:[1,0]
	v_lshlrev_b32_e32 v164, 16, v201
	v_and_b32_e32 v165, 0xffff0000, v201
	v_rcp_f32_e32 v128, v128
	v_rcp_f32_e32 v129, v129
	v_pk_fma_f32 v[134:135], v[126:127], v[156:157], v[134:135]
	v_pk_fma_f32 v[136:137], v[128:129], v[164:165], v[136:137]
	v_pk_add_f32 v[94:95], v[94:95], 1.0 op_sel_hi:[1,0]
	v_lshlrev_b32_e32 v156, 16, v202
	v_and_b32_e32 v157, 0xffff0000, v202
	v_rcp_f32_e32 v94, v94
	v_rcp_f32_e32 v95, v95
	v_pk_add_f32 v[96:97], v[96:97], 1.0 op_sel_hi:[1,0]
	v_lshlrev_b32_e32 v164, 16, v203
	v_and_b32_e32 v165, 0xffff0000, v203
	v_rcp_f32_e32 v96, v96
	v_rcp_f32_e32 v97, v97
	v_pk_fma_f32 v[134:135], v[94:95], v[156:157], v[134:135]
	v_pk_fma_f32 v[136:137], v[96:97], v[164:165], v[136:137]
	v_pk_add_f32 v[90:91], v[90:91], 1.0 op_sel_hi:[1,0]
	v_lshlrev_b32_e32 v156, 16, v204
	v_and_b32_e32 v157, 0xffff0000, v204
	v_rcp_f32_e32 v90, v90
	v_rcp_f32_e32 v91, v91
	v_pk_add_f32 v[92:93], v[92:93], 1.0 op_sel_hi:[1,0]
	v_lshlrev_b32_e32 v164, 16, v205
	v_and_b32_e32 v165, 0xffff0000, v205
	v_rcp_f32_e32 v92, v92
	v_rcp_f32_e32 v93, v93
	v_pk_fma_f32 v[134:135], v[90:91], v[156:157], v[134:135]
	v_pk_fma_f32 v[136:137], v[92:93], v[164:165], v[136:137]
	s_waitcnt vmcnt(16)
; DI float sigm(float x) { return 1.f / (1.f + __expf(-x)); }
; DI void gate_reg(PREF p, int l, int n, f32x4 (&acc)[2][2][4][2], int dt) {
;     ...
; #pragma unroll
;       for (int m = 0; m < 4; ++m) {
;         float b[8]; unpack8(bn[m], b);
;         float v[8];
; #pragma unroll
;         for (int nn = 0; nn < 2; ++nn)
; #pragma unroll
;           for (int j = 0; j < 4; ++j) v[nn * 4 + j] = sigm(acc[ai][bj][m][nn][j] + bias[bj][nn]) * b[nn * 4 + j];
;         if (n > 0) {
;           float o[8]; unpack8(pv[m], o);
; #pragma unroll
;           for (int e = 0; e < 8; ++e) v[e] += o[e];
	v_add_f32_e32 v122, v122, v170
	v_mul_f32_e32 v122, 0xbfb8aa3b, v122
	v_exp_f32_e32 v122, v122
	v_add_f32_e32 v123, v123, v170
	v_mul_f32_e32 v123, 0xbfb8aa3b, v123
	v_exp_f32_e32 v123, v123
	v_add_f32_e32 v124, v124, v170
	v_mul_f32_e32 v124, 0xbfb8aa3b, v124
	v_exp_f32_e32 v124, v124
	v_add_f32_e32 v125, v125, v170
	v_mul_f32_e32 v125, 0xbfb8aa3b, v125
	v_exp_f32_e32 v125, v125
	v_add_f32_e32 v114, v114, v252
	v_mul_f32_e32 v114, 0xbfb8aa3b, v114
	v_exp_f32_e32 v114, v114
	v_add_f32_e32 v115, v115, v252
	v_mul_f32_e32 v115, 0xbfb8aa3b, v115
	v_exp_f32_e32 v115, v115
	v_add_f32_e32 v116, v116, v252
	v_mul_f32_e32 v116, 0xbfb8aa3b, v116
	v_exp_f32_e32 v116, v116
	v_add_f32_e32 v117, v117, v252
	v_mul_f32_e32 v117, 0xbfb8aa3b, v117
	v_exp_f32_e32 v117, v117
	v_add_f32_e32 v86, v86, v253
	v_mul_f32_e32 v86, 0xbfb8aa3b, v86
	v_exp_f32_e32 v86, v86
	v_add_f32_e32 v87, v87, v253
	v_mul_f32_e32 v87, 0xbfb8aa3b, v87
	v_exp_f32_e32 v87, v87
	v_add_f32_e32 v88, v88, v253
	v_mul_f32_e32 v88, 0xbfb8aa3b, v88
	v_exp_f32_e32 v88, v88
	v_add_f32_e32 v89, v89, v253
	v_mul_f32_e32 v89, 0xbfb8aa3b, v89
	v_exp_f32_e32 v89, v89
	v_add_f32_e32 v82, v82, v162
	v_mul_f32_e32 v82, 0xbfb8aa3b, v82
	v_exp_f32_e32 v82, v82
	v_add_f32_e32 v83, v83, v162
	v_mul_f32_e32 v83, 0xbfb8aa3b, v83
	v_exp_f32_e32 v83, v83
	v_add_f32_e32 v84, v84, v162
	v_mul_f32_e32 v84, 0xbfb8aa3b, v84
	v_exp_f32_e32 v84, v84
	v_add_f32_e32 v85, v85, v162
	v_mul_f32_e32 v85, 0xbfb8aa3b, v85
	v_exp_f32_e32 v85, v85
	v_pk_add_f32 v[122:123], v[122:123], 1.0 op_sel_hi:[1,0]
	v_lshlrev_b32_e32 v156, 16, v206
	v_and_b32_e32 v157, 0xffff0000, v206
	v_rcp_f32_e32 v122, v122
	v_rcp_f32_e32 v123, v123
	v_pk_add_f32 v[124:125], v[124:125], 1.0 op_sel_hi:[1,0]
	v_lshlrev_b32_e32 v164, 16, v207
	v_and_b32_e32 v165, 0xffff0000, v207
	v_rcp_f32_e32 v124, v124
	v_rcp_f32_e32 v125, v125
	v_pk_mul_f32 v[122:123], v[122:123], v[156:157]
	v_pk_mul_f32 v[124:125], v[124:125], v[164:165]
	v_pk_add_f32 v[114:115], v[114:115], 1.0 op_sel_hi:[1,0]
	v_lshlrev_b32_e32 v156, 16, v208
	v_and_b32_e32 v157, 0xffff0000, v208
	v_rcp_f32_e32 v114, v114
	v_rcp_f32_e32 v115, v115
	v_pk_add_f32 v[116:117], v[116:117], 1.0 op_sel_hi:[1,0]
	v_lshlrev_b32_e32 v164, 16, v209
	v_and_b32_e32 v165, 0xffff0000, v209
	v_rcp_f32_e32 v116, v116
	v_rcp_f32_e32 v117, v117
	v_pk_fma_f32 v[122:123], v[114:115], v[156:157], v[122:123]
	v_pk_fma_f32 v[124:125], v[116:117], v[164:165], v[124:125]
	v_pk_add_f32 v[86:87], v[86:87], 1.0 op_sel_hi:[1,0]
	v_lshlrev_b32_e32 v156, 16, v210
	v_and_b32_e32 v157, 0xffff0000, v210
	v_rcp_f32_e32 v86, v86
	v_rcp_f32_e32 v87, v87
	v_pk_add_f32 v[88:89], v[88:89], 1.0 op_sel_hi:[1,0]
	v_lshlrev_b32_e32 v164, 16, v211
	v_and_b32_e32 v165, 0xffff0000, v211
	v_rcp_f32_e32 v88, v88
	v_rcp_f32_e32 v89, v89
	v_pk_fma_f32 v[122:123], v[86:87], v[156:157], v[122:123]
	v_pk_fma_f32 v[124:125], v[88:89], v[164:165], v[124:125]
	v_pk_add_f32 v[82:83], v[82:83], 1.0 op_sel_hi:[1,0]
	v_lshlrev_b32_e32 v156, 16, v212
	v_and_b32_e32 v157, 0xffff0000, v212
	v_rcp_f32_e32 v82, v82
	v_rcp_f32_e32 v83, v83
	v_pk_add_f32 v[84:85], v[84:85], 1.0 op_sel_hi:[1,0]
	v_lshlrev_b32_e32 v164, 16, v213
	v_and_b32_e32 v165, 0xffff0000, v213
	v_rcp_f32_e32 v84, v84
	v_rcp_f32_e32 v85, v85
	v_pk_fma_f32 v[122:123], v[82:83], v[156:157], v[122:123]
	v_pk_fma_f32 v[124:125], v[84:85], v[164:165], v[124:125]
	s_waitcnt vmcnt(12)
	v_add_f32_e32 v78, v78, v170
	v_mul_f32_e32 v78, 0xbfb8aa3b, v78
	v_exp_f32_e32 v78, v78
	v_add_f32_e32 v79, v79, v170
	v_mul_f32_e32 v79, 0xbfb8aa3b, v79
	v_exp_f32_e32 v79, v79
	v_add_f32_e32 v80, v80, v170
	v_mul_f32_e32 v80, 0xbfb8aa3b, v80
	v_exp_f32_e32 v80, v80
	v_add_f32_e32 v81, v81, v170
	v_mul_f32_e32 v81, 0xbfb8aa3b, v81
	v_exp_f32_e32 v81, v81
	v_add_f32_e32 v74, v74, v252
	v_mul_f32_e32 v74, 0xbfb8aa3b, v74
	v_exp_f32_e32 v74, v74
	v_add_f32_e32 v75, v75, v252
	v_mul_f32_e32 v75, 0xbfb8aa3b, v75
	v_exp_f32_e32 v75, v75
	v_add_f32_e32 v76, v76, v252
	v_mul_f32_e32 v76, 0xbfb8aa3b, v76
	v_exp_f32_e32 v76, v76
	v_add_f32_e32 v77, v77, v252
	v_mul_f32_e32 v77, 0xbfb8aa3b, v77
	v_exp_f32_e32 v77, v77
	v_add_f32_e32 v46, v46, v253
	v_mul_f32_e32 v46, 0xbfb8aa3b, v46
	v_exp_f32_e32 v46, v46
	v_add_f32_e32 v47, v47, v253
	v_mul_f32_e32 v47, 0xbfb8aa3b, v47
	v_exp_f32_e32 v47, v47
	v_add_f32_e32 v48, v48, v253
	v_mul_f32_e32 v48, 0xbfb8aa3b, v48
	v_exp_f32_e32 v48, v48
	v_add_f32_e32 v49, v49, v253
	v_mul_f32_e32 v49, 0xbfb8aa3b, v49
	v_exp_f32_e32 v49, v49
	v_add_f32_e32 v38, v38, v162
	v_mul_f32_e32 v38, 0xbfb8aa3b, v38
	v_exp_f32_e32 v38, v38
	v_add_f32_e32 v39, v39, v162
	v_mul_f32_e32 v39, 0xbfb8aa3b, v39
	v_exp_f32_e32 v39, v39
	v_add_f32_e32 v40, v40, v162
	v_mul_f32_e32 v40, 0xbfb8aa3b, v40
	v_exp_f32_e32 v40, v40
	v_add_f32_e32 v41, v41, v162
	v_mul_f32_e32 v41, 0xbfb8aa3b, v41
	v_exp_f32_e32 v41, v41
	v_pk_add_f32 v[78:79], v[78:79], 1.0 op_sel_hi:[1,0]
	v_lshlrev_b32_e32 v156, 16, v214
	v_and_b32_e32 v157, 0xffff0000, v214
	v_rcp_f32_e32 v78, v78
	v_rcp_f32_e32 v79, v79
	v_pk_add_f32 v[80:81], v[80:81], 1.0 op_sel_hi:[1,0]
	v_lshlrev_b32_e32 v164, 16, v215
	v_and_b32_e32 v165, 0xffff0000, v215
	v_rcp_f32_e32 v80, v80
	v_rcp_f32_e32 v81, v81
	v_pk_mul_f32 v[78:79], v[78:79], v[156:157]
	v_pk_mul_f32 v[80:81], v[80:81], v[164:165]
	v_pk_add_f32 v[74:75], v[74:75], 1.0 op_sel_hi:[1,0]
	v_lshlrev_b32_e32 v156, 16, v216
	v_and_b32_e32 v157, 0xffff0000, v216
	v_rcp_f32_e32 v74, v74
	v_rcp_f32_e32 v75, v75
	v_pk_add_f32 v[76:77], v[76:77], 1.0 op_sel_hi:[1,0]
	v_lshlrev_b32_e32 v164, 16, v217
	v_and_b32_e32 v165, 0xffff0000, v217
	v_rcp_f32_e32 v76, v76
	v_rcp_f32_e32 v77, v77
	v_pk_fma_f32 v[78:79], v[74:75], v[156:157], v[78:79]
	v_pk_fma_f32 v[80:81], v[76:77], v[164:165], v[80:81]
	v_pk_add_f32 v[46:47], v[46:47], 1.0 op_sel_hi:[1,0]
	v_lshlrev_b32_e32 v156, 16, v218
	v_and_b32_e32 v157, 0xffff0000, v218
	v_rcp_f32_e32 v46, v46
	v_rcp_f32_e32 v47, v47
	v_pk_add_f32 v[48:49], v[48:49], 1.0 op_sel_hi:[1,0]
	v_lshlrev_b32_e32 v164, 16, v219
	v_and_b32_e32 v165, 0xffff0000, v219
	v_rcp_f32_e32 v48, v48
	v_rcp_f32_e32 v49, v49
	v_pk_fma_f32 v[78:79], v[46:47], v[156:157], v[78:79]
	v_pk_fma_f32 v[80:81], v[48:49], v[164:165], v[80:81]
	v_pk_add_f32 v[38:39], v[38:39], 1.0 op_sel_hi:[1,0]
	v_lshlrev_b32_e32 v156, 16, v220
	v_and_b32_e32 v157, 0xffff0000, v220
	v_rcp_f32_e32 v38, v38
	v_rcp_f32_e32 v39, v39
	v_pk_add_f32 v[40:41], v[40:41], 1.0 op_sel_hi:[1,0]
	v_lshlrev_b32_e32 v164, 16, v221
	v_and_b32_e32 v165, 0xffff0000, v221
	v_rcp_f32_e32 v40, v40
	v_rcp_f32_e32 v41, v41
	v_pk_fma_f32 v[78:79], v[38:39], v[156:157], v[78:79]
	v_pk_fma_f32 v[80:81], v[40:41], v[164:165], v[80:81]
	s_waitcnt vmcnt(8)
; DI float sigm(float x) { return 1.f / (1.f + __expf(-x)); }
; DI void gate_reg(PREF p, int l, int n, f32x4 (&acc)[2][2][4][2], int dt) {
;     ...
; #pragma unroll
;       for (int m = 0; m < 4; ++m) {
;         float b[8]; unpack8(bn[m], b);
;         float v[8];
; #pragma unroll
;         for (int nn = 0; nn < 2; ++nn)
; #pragma unroll
;           for (int j = 0; j < 4; ++j) v[nn * 4 + j] = sigm(acc[ai][bj][m][nn][j] + bias[bj][nn]) * b[nn * 4 + j];
;         if (n > 0) {
;           float o[8]; unpack8(pv[m], o);
; #pragma unroll
;           for (int e = 0; e < 8; ++e) v[e] += o[e];
	v_add_f32_e32 v70, v70, v170
	v_mul_f32_e32 v70, 0xbfb8aa3b, v70
	v_exp_f32_e32 v70, v70
	v_add_f32_e32 v71, v71, v170
	v_mul_f32_e32 v71, 0xbfb8aa3b, v71
	v_exp_f32_e32 v71, v71
	v_add_f32_e32 v72, v72, v170
	v_mul_f32_e32 v72, 0xbfb8aa3b, v72
	v_exp_f32_e32 v72, v72
	v_add_f32_e32 v73, v73, v170
	v_mul_f32_e32 v73, 0xbfb8aa3b, v73
	v_exp_f32_e32 v73, v73
	v_add_f32_e32 v66, v66, v252
	v_mul_f32_e32 v66, 0xbfb8aa3b, v66
	v_exp_f32_e32 v66, v66
	v_add_f32_e32 v67, v67, v252
	v_mul_f32_e32 v67, 0xbfb8aa3b, v67
	v_exp_f32_e32 v67, v67
	v_add_f32_e32 v68, v68, v252
	v_mul_f32_e32 v68, 0xbfb8aa3b, v68
	v_exp_f32_e32 v68, v68
	v_add_f32_e32 v69, v69, v252
	v_mul_f32_e32 v69, 0xbfb8aa3b, v69
	v_exp_f32_e32 v69, v69
	v_add_f32_e32 v34, v34, v253
	v_mul_f32_e32 v34, 0xbfb8aa3b, v34
	v_exp_f32_e32 v34, v34
	v_add_f32_e32 v35, v35, v253
	v_mul_f32_e32 v35, 0xbfb8aa3b, v35
	v_exp_f32_e32 v35, v35
	v_add_f32_e32 v36, v36, v253
	v_mul_f32_e32 v36, 0xbfb8aa3b, v36
	v_exp_f32_e32 v36, v36
	v_add_f32_e32 v37, v37, v253
	v_mul_f32_e32 v37, 0xbfb8aa3b, v37
	v_exp_f32_e32 v37, v37
	v_add_f32_e32 v26, v26, v162
	v_mul_f32_e32 v26, 0xbfb8aa3b, v26
	v_exp_f32_e32 v26, v26
	v_add_f32_e32 v27, v27, v162
	v_mul_f32_e32 v27, 0xbfb8aa3b, v27
	v_exp_f32_e32 v27, v27
	v_add_f32_e32 v28, v28, v162
	v_mul_f32_e32 v28, 0xbfb8aa3b, v28
	v_exp_f32_e32 v28, v28
	v_add_f32_e32 v29, v29, v162
	v_mul_f32_e32 v29, 0xbfb8aa3b, v29
	v_exp_f32_e32 v29, v29
	v_pk_add_f32 v[70:71], v[70:71], 1.0 op_sel_hi:[1,0]
	v_lshlrev_b32_e32 v156, 16, v222
	v_and_b32_e32 v157, 0xffff0000, v222
	v_rcp_f32_e32 v70, v70
	v_rcp_f32_e32 v71, v71
	v_pk_add_f32 v[72:73], v[72:73], 1.0 op_sel_hi:[1,0]
	v_lshlrev_b32_e32 v164, 16, v223
	v_and_b32_e32 v165, 0xffff0000, v223
	v_rcp_f32_e32 v72, v72
	v_rcp_f32_e32 v73, v73
	v_pk_mul_f32 v[70:71], v[70:71], v[156:157]
	v_pk_mul_f32 v[72:73], v[72:73], v[164:165]
	v_pk_add_f32 v[66:67], v[66:67], 1.0 op_sel_hi:[1,0]
	v_lshlrev_b32_e32 v156, 16, v224
	v_and_b32_e32 v157, 0xffff0000, v224
	v_rcp_f32_e32 v66, v66
	v_rcp_f32_e32 v67, v67
	v_pk_add_f32 v[68:69], v[68:69], 1.0 op_sel_hi:[1,0]
	v_lshlrev_b32_e32 v164, 16, v225
	v_and_b32_e32 v165, 0xffff0000, v225
	v_rcp_f32_e32 v68, v68
	v_rcp_f32_e32 v69, v69
	v_pk_fma_f32 v[70:71], v[66:67], v[156:157], v[70:71]
	v_pk_fma_f32 v[72:73], v[68:69], v[164:165], v[72:73]
	v_pk_add_f32 v[34:35], v[34:35], 1.0 op_sel_hi:[1,0]
	v_lshlrev_b32_e32 v156, 16, v226
	v_and_b32_e32 v157, 0xffff0000, v226
	v_rcp_f32_e32 v34, v34
	v_rcp_f32_e32 v35, v35
	v_pk_add_f32 v[36:37], v[36:37], 1.0 op_sel_hi:[1,0]
	v_lshlrev_b32_e32 v164, 16, v227
	v_and_b32_e32 v165, 0xffff0000, v227
	v_rcp_f32_e32 v36, v36
	v_rcp_f32_e32 v37, v37
	v_pk_fma_f32 v[70:71], v[34:35], v[156:157], v[70:71]
	v_pk_fma_f32 v[72:73], v[36:37], v[164:165], v[72:73]
	v_pk_add_f32 v[26:27], v[26:27], 1.0 op_sel_hi:[1,0]
	v_lshlrev_b32_e32 v156, 16, v228
	v_and_b32_e32 v157, 0xffff0000, v228
	v_rcp_f32_e32 v26, v26
	v_rcp_f32_e32 v27, v27
	v_pk_add_f32 v[28:29], v[28:29], 1.0 op_sel_hi:[1,0]
	v_lshlrev_b32_e32 v164, 16, v229
	v_and_b32_e32 v165, 0xffff0000, v229
	v_rcp_f32_e32 v28, v28
	v_rcp_f32_e32 v29, v29
	v_pk_fma_f32 v[70:71], v[26:27], v[156:157], v[70:71]
	v_pk_fma_f32 v[72:73], v[28:29], v[164:165], v[72:73]
	s_waitcnt vmcnt(4)
	v_add_f32_e32 v62, v62, v170
	v_mul_f32_e32 v62, 0xbfb8aa3b, v62
	v_exp_f32_e32 v62, v62
	v_add_f32_e32 v63, v63, v170
	v_mul_f32_e32 v63, 0xbfb8aa3b, v63
	v_exp_f32_e32 v63, v63
	v_add_f32_e32 v64, v64, v170
	v_mul_f32_e32 v64, 0xbfb8aa3b, v64
	v_exp_f32_e32 v64, v64
	v_add_f32_e32 v65, v65, v170
	v_mul_f32_e32 v65, 0xbfb8aa3b, v65
	v_exp_f32_e32 v65, v65
	v_add_f32_e32 v58, v58, v252
	v_mul_f32_e32 v58, 0xbfb8aa3b, v58
	v_exp_f32_e32 v58, v58
	v_add_f32_e32 v59, v59, v252
	v_mul_f32_e32 v59, 0xbfb8aa3b, v59
	v_exp_f32_e32 v59, v59
	v_add_f32_e32 v60, v60, v252
	v_mul_f32_e32 v60, 0xbfb8aa3b, v60
	v_exp_f32_e32 v60, v60
	v_add_f32_e32 v61, v61, v252
	v_mul_f32_e32 v61, 0xbfb8aa3b, v61
	v_exp_f32_e32 v61, v61
	v_add_f32_e32 v22, v22, v253
	v_mul_f32_e32 v22, 0xbfb8aa3b, v22
	v_exp_f32_e32 v22, v22
	v_add_f32_e32 v23, v23, v253
	v_mul_f32_e32 v23, 0xbfb8aa3b, v23
	v_exp_f32_e32 v23, v23
	v_add_f32_e32 v24, v24, v253
	v_mul_f32_e32 v24, 0xbfb8aa3b, v24
	v_exp_f32_e32 v24, v24
	v_add_f32_e32 v25, v25, v253
	v_mul_f32_e32 v25, 0xbfb8aa3b, v25
	v_exp_f32_e32 v25, v25
	v_add_f32_e32 v14, v14, v162
	v_mul_f32_e32 v14, 0xbfb8aa3b, v14
	v_exp_f32_e32 v14, v14
	v_add_f32_e32 v15, v15, v162
	v_mul_f32_e32 v15, 0xbfb8aa3b, v15
	v_exp_f32_e32 v15, v15
	v_add_f32_e32 v16, v16, v162
	v_mul_f32_e32 v16, 0xbfb8aa3b, v16
	v_exp_f32_e32 v16, v16
	v_add_f32_e32 v17, v17, v162
	v_mul_f32_e32 v17, 0xbfb8aa3b, v17
	v_exp_f32_e32 v17, v17
	v_pk_add_f32 v[62:63], v[62:63], 1.0 op_sel_hi:[1,0]
	v_lshlrev_b32_e32 v156, 16, v182
	v_and_b32_e32 v157, 0xffff0000, v182
	v_rcp_f32_e32 v62, v62
	v_rcp_f32_e32 v63, v63
	v_pk_add_f32 v[64:65], v[64:65], 1.0 op_sel_hi:[1,0]
	v_lshlrev_b32_e32 v164, 16, v183
	v_and_b32_e32 v165, 0xffff0000, v183
	v_rcp_f32_e32 v64, v64
	v_rcp_f32_e32 v65, v65
	v_pk_mul_f32 v[62:63], v[62:63], v[156:157]
	v_pk_mul_f32 v[64:65], v[64:65], v[164:165]
	v_pk_add_f32 v[58:59], v[58:59], 1.0 op_sel_hi:[1,0]
	v_lshlrev_b32_e32 v156, 16, v184
	v_and_b32_e32 v157, 0xffff0000, v184
	v_rcp_f32_e32 v58, v58
	v_rcp_f32_e32 v59, v59
	v_pk_add_f32 v[60:61], v[60:61], 1.0 op_sel_hi:[1,0]
	v_lshlrev_b32_e32 v164, 16, v185
	v_and_b32_e32 v165, 0xffff0000, v185
	v_rcp_f32_e32 v60, v60
	v_rcp_f32_e32 v61, v61
	v_pk_fma_f32 v[62:63], v[58:59], v[156:157], v[62:63]
	v_pk_fma_f32 v[64:65], v[60:61], v[164:165], v[64:65]
	v_pk_add_f32 v[22:23], v[22:23], 1.0 op_sel_hi:[1,0]
	v_lshlrev_b32_e32 v156, 16, v186
	v_and_b32_e32 v157, 0xffff0000, v186
	v_rcp_f32_e32 v22, v22
	v_rcp_f32_e32 v23, v23
	v_pk_add_f32 v[24:25], v[24:25], 1.0 op_sel_hi:[1,0]
	v_lshlrev_b32_e32 v164, 16, v187
	v_and_b32_e32 v165, 0xffff0000, v187
	v_rcp_f32_e32 v24, v24
	v_rcp_f32_e32 v25, v25
	v_pk_fma_f32 v[62:63], v[22:23], v[156:157], v[62:63]
	v_pk_fma_f32 v[64:65], v[24:25], v[164:165], v[64:65]
	v_pk_add_f32 v[14:15], v[14:15], 1.0 op_sel_hi:[1,0]
	v_lshlrev_b32_e32 v156, 16, v188
	v_and_b32_e32 v157, 0xffff0000, v188
	v_rcp_f32_e32 v14, v14
	v_rcp_f32_e32 v15, v15
	v_pk_add_f32 v[16:17], v[16:17], 1.0 op_sel_hi:[1,0]
	v_lshlrev_b32_e32 v164, 16, v189
	v_and_b32_e32 v165, 0xffff0000, v189
	v_rcp_f32_e32 v16, v16
	v_rcp_f32_e32 v17, v17
	v_pk_fma_f32 v[62:63], v[14:15], v[156:157], v[62:63]
	v_pk_fma_f32 v[64:65], v[16:17], v[164:165], v[64:65]
	s_waitcnt vmcnt(0)
; DI float sigm(float x) { return 1.f / (1.f + __expf(-x)); }
; DI u32x4 pack8(const float* f) { u32x4 o; o.x = pack2(f[0], f[1]); o.y = pack2(f[2], f[3]); o.z = pack2(f[4], f[5]); o.w = pack2(f[6], f[7]); return o; }
; DI int tid512() { int t = threadIdx.x; asm volatile("" : "+v"(t)); return t; }
; DI void gate_reg(PREF p, int l, int n, f32x4 (&acc)[2][2][4][2], int dt) {
;     ...
;         float b[8]; unpack8(bn[m], b);
;         float v[8];
; #pragma unroll
;         for (int nn = 0; nn < 2; ++nn)
; #pragma unroll
;           for (int j = 0; j < 4; ++j) v[nn * 4 + j] = sigm(acc[ai][bj][m][nn][j] + bias[bj][nn]) * b[nn * 4 + j];
;         if (n > 0) {
;           float o[8]; unpack8(pv[m], o);
; #pragma unroll
;           for (int e = 0; e < 8; ++e) v[e] += o[e];
;         }
;         if (n < 3) ssum[((ai * 2 + bj) * 4 + m) * 64] = pack8(v);
; #pragma unroll
;         for (int nn = 0; nn < 2; ++nn)
; #pragma unroll
;           for (int j = 0; j < 4; ++j) acc[ai][bj][m][nn][j] = v[nn * 4 + j];
; template <int AI, int BJ>
; DI void mg_quadrant(PREF p, const f32x4 (&acc)[2][2][4][2], int mt, int dt, float* Cs) {
;   const int t = tid512();
;   const int row0 = mt * 256 + AI * 128, col0 = dt * 256 + BJ * 128;
;   stage_q<AI, BJ>(acc, Cs);
; #pragma unroll
;   for (int q = 0; q < 4; ++q) {
;     int r = (t >> 4) + 32 * q, c = (t & 15) * 8;
;     float v[8]; ld8(Cs + r * CST + c, v);
;     *(u32x4*)(p.mg + (size_t)(row0 + r) * 1024 + col0 + c) = pack8(v);
;   }
	v_add_f32_e32 v54, v54, v170
	v_mul_f32_e32 v54, 0xbfb8aa3b, v54
	v_exp_f32_e32 v54, v54
	v_add_f32_e32 v55, v55, v170
	v_mul_f32_e32 v55, 0xbfb8aa3b, v55
	v_exp_f32_e32 v55, v55
	v_add_f32_e32 v56, v56, v170
	v_mul_f32_e32 v56, 0xbfb8aa3b, v56
	v_exp_f32_e32 v56, v56
	v_add_f32_e32 v57, v57, v170
	v_mul_f32_e32 v57, 0xbfb8aa3b, v57
	v_exp_f32_e32 v57, v57
	v_add_f32_e32 v50, v50, v252
	v_mul_f32_e32 v50, 0xbfb8aa3b, v50
	v_exp_f32_e32 v50, v50
	v_add_f32_e32 v51, v51, v252
	v_mul_f32_e32 v51, 0xbfb8aa3b, v51
	v_exp_f32_e32 v51, v51
	v_add_f32_e32 v52, v52, v252
	v_mul_f32_e32 v52, 0xbfb8aa3b, v52
	v_exp_f32_e32 v52, v52
	v_add_f32_e32 v53, v53, v252
	v_mul_f32_e32 v53, 0xbfb8aa3b, v53
	v_exp_f32_e32 v53, v53
	v_add_f32_e32 v10, v10, v253
	v_mul_f32_e32 v10, 0xbfb8aa3b, v10
	v_exp_f32_e32 v10, v10
	v_add_f32_e32 v11, v11, v253
	v_mul_f32_e32 v11, 0xbfb8aa3b, v11
	v_exp_f32_e32 v11, v11
	v_add_f32_e32 v12, v12, v253
	v_mul_f32_e32 v12, 0xbfb8aa3b, v12
	v_exp_f32_e32 v12, v12
	v_add_f32_e32 v13, v13, v253
	v_mul_f32_e32 v13, 0xbfb8aa3b, v13
	v_exp_f32_e32 v13, v13
	v_add_f32_e32 v2, v2, v162
	v_mul_f32_e32 v2, 0xbfb8aa3b, v2
	v_exp_f32_e32 v2, v2
	v_add_f32_e32 v3, v3, v162
	v_mul_f32_e32 v3, 0xbfb8aa3b, v3
	v_exp_f32_e32 v3, v3
	v_add_f32_e32 v4, v4, v162
	v_mul_f32_e32 v4, 0xbfb8aa3b, v4
	v_exp_f32_e32 v4, v4
	v_add_f32_e32 v5, v5, v162
	v_mul_f32_e32 v5, 0xbfb8aa3b, v5
	v_exp_f32_e32 v5, v5
	v_pk_add_f32 v[54:55], v[54:55], 1.0 op_sel_hi:[1,0]
	v_lshlrev_b32_e32 v156, 16, v190
	v_and_b32_e32 v157, 0xffff0000, v190
	v_rcp_f32_e32 v54, v54
	v_rcp_f32_e32 v55, v55
	v_pk_add_f32 v[56:57], v[56:57], 1.0 op_sel_hi:[1,0]
	v_lshlrev_b32_e32 v164, 16, v191
	v_and_b32_e32 v165, 0xffff0000, v191
	v_rcp_f32_e32 v56, v56
	v_rcp_f32_e32 v57, v57
	v_pk_mul_f32 v[54:55], v[54:55], v[156:157]
	v_pk_mul_f32 v[56:57], v[56:57], v[164:165]
	v_pk_add_f32 v[50:51], v[50:51], 1.0 op_sel_hi:[1,0]
	v_lshlrev_b32_e32 v156, 16, v192
	v_and_b32_e32 v157, 0xffff0000, v192
	v_rcp_f32_e32 v50, v50
	v_rcp_f32_e32 v51, v51
	v_pk_add_f32 v[52:53], v[52:53], 1.0 op_sel_hi:[1,0]
	v_lshlrev_b32_e32 v164, 16, v193
	v_and_b32_e32 v165, 0xffff0000, v193
	v_rcp_f32_e32 v52, v52
	v_rcp_f32_e32 v53, v53
	v_pk_fma_f32 v[54:55], v[50:51], v[156:157], v[54:55]
	v_pk_fma_f32 v[56:57], v[52:53], v[164:165], v[56:57]
	v_pk_add_f32 v[10:11], v[10:11], 1.0 op_sel_hi:[1,0]
	v_lshlrev_b32_e32 v156, 16, v194
	v_and_b32_e32 v157, 0xffff0000, v194
	v_rcp_f32_e32 v10, v10
	v_rcp_f32_e32 v11, v11
	v_pk_add_f32 v[12:13], v[12:13], 1.0 op_sel_hi:[1,0]
	v_lshlrev_b32_e32 v164, 16, v195
	v_and_b32_e32 v165, 0xffff0000, v195
	v_rcp_f32_e32 v12, v12
	v_rcp_f32_e32 v13, v13
	v_pk_fma_f32 v[54:55], v[10:11], v[156:157], v[54:55]
	v_pk_fma_f32 v[56:57], v[12:13], v[164:165], v[56:57]
	v_pk_add_f32 v[2:3], v[2:3], 1.0 op_sel_hi:[1,0]
	v_lshlrev_b32_e32 v156, 16, v196
	v_and_b32_e32 v157, 0xffff0000, v196
	v_rcp_f32_e32 v2, v2
	v_rcp_f32_e32 v3, v3
	v_pk_add_f32 v[4:5], v[4:5], 1.0 op_sel_hi:[1,0]
	v_lshlrev_b32_e32 v164, 16, v197
	v_and_b32_e32 v165, 0xffff0000, v197
	v_rcp_f32_e32 v4, v4
	v_rcp_f32_e32 v5, v5
	v_pk_fma_f32 v[54:55], v[2:3], v[156:157], v[54:55]
	v_pk_fma_f32 v[56:57], v[4:5], v[164:165], v[56:57]
	v_lshrrev_b32_e32 v156, 8, v168
	v_lshlrev_b32_e32 v156, 6, v156
	v_bfe_u32 v157, v168, 4, 2
	v_lshl_add_u32 v156, v157, 2, v156
	v_mul_u32_u24_e32 v156, 0x84, v156
	v_lshlrev_b32_e32 v157, 4, v155
	v_and_b32_e32 v164, 15, v168
	v_add3_u32 v156, v156, v157, v164
	v_lshlrev_b32_e32 v156, 2, v156
	v_lshrrev_b32_e32 v157, 3, v168
	v_lshlrev_b32_e32 v165, 11, v157
	v_mul_u32_u24_e32 v157, 0x84, v157
	v_and_b32_e32 v164, 7, v168
	v_lshl_add_u32 v157, v164, 3, v157
	v_lshlrev_b32_e32 v157, 2, v157
	v_lshl_add_u32 v165, v164, 4, v165
	v_mov_b32_e32 v164, v165
	s_waitcnt lgkmcnt(0)
	s_barrier
	ds_write_b32 v156, v158 offset:0
	ds_write_b32 v156, v159 offset:528
	ds_write_b32 v156, v160 offset:1056
	ds_write_b32 v156, v161 offset:1584
	ds_write_b32 v156, v146 offset:8448
	ds_write_b32 v156, v147 offset:8976
	ds_write_b32 v156, v148 offset:9504
	ds_write_b32 v156, v149 offset:10032
	ds_write_b32 v156, v134 offset:16896
	ds_write_b32 v156, v135 offset:17424
	ds_write_b32 v156, v136 offset:17952
	ds_write_b32 v156, v137 offset:18480
	ds_write_b32 v156, v122 offset:25344
	ds_write_b32 v156, v123 offset:25872
	ds_write_b32 v156, v124 offset:26400
	ds_write_b32 v156, v125 offset:26928
	s_waitcnt lgkmcnt(0)
	s_barrier
	s_add_i32 s0, s12, 0
	s_lshl_b32 s0, s0, 11
	s_lshl_b32 s1, s23, 7
	s_add_u32 s0, s0, s1
	s_add_u32 s0, s36, s0
	s_addc_u32 s1, s37, 0
	ds_read_b128 v[230:233], v157 offset:0
	ds_read_b128 v[234:237], v157 offset:16
	ds_read_b128 v[238:241], v157 offset:33792
	ds_read_b128 v[242:245], v157 offset:33808
	s_waitcnt lgkmcnt(2)
	v_cvt_pk_bf16_f32 v230, v230, v231
	v_cvt_pk_bf16_f32 v231, v232, v233
	v_cvt_pk_bf16_f32 v232, v234, v235
	v_cvt_pk_bf16_f32 v233, v236, v237
	global_store_dwordx4 v164, v[230:233], s[0:1]
	s_waitcnt lgkmcnt(0)
	v_cvt_pk_bf16_f32 v238, v238, v239
	v_cvt_pk_bf16_f32 v239, v240, v241
	v_cvt_pk_bf16_f32 v240, v242, v243
	v_cvt_pk_bf16_f32 v241, v244, v245
	v_add_u32_e32 v164, 0x20000, v164
	global_store_dwordx4 v164, v[238:241], s[0:1]
	v_mov_b32_e32 v164, v165
	s_waitcnt lgkmcnt(0)
	s_barrier
	ds_write_b32 v156, v78 offset:0
	ds_write_b32 v156, v79 offset:528
	ds_write_b32 v156, v80 offset:1056
	ds_write_b32 v156, v81 offset:1584
	ds_write_b32 v156, v70 offset:8448
	ds_write_b32 v156, v71 offset:8976
	ds_write_b32 v156, v72 offset:9504
	ds_write_b32 v156, v73 offset:10032
	ds_write_b32 v156, v62 offset:16896
	ds_write_b32 v156, v63 offset:17424
	ds_write_b32 v156, v64 offset:17952
	ds_write_b32 v156, v65 offset:18480
	ds_write_b32 v156, v54 offset:25344
	ds_write_b32 v156, v55 offset:25872
	ds_write_b32 v156, v56 offset:26400
	ds_write_b32 v156, v57 offset:26928
	s_waitcnt lgkmcnt(0)
	s_barrier
	s_add_i32 s0, s12, 128
	s_lshl_b32 s0, s0, 11
	s_lshl_b32 s1, s23, 7
	s_add_u32 s0, s0, s1
	s_add_u32 s0, s36, s0
	s_addc_u32 s1, s37, 0
	ds_read_b128 v[230:233], v157 offset:0
	ds_read_b128 v[234:237], v157 offset:16
	ds_read_b128 v[238:241], v157 offset:33792
	ds_read_b128 v[242:245], v157 offset:33808
	s_waitcnt lgkmcnt(2)
	v_cvt_pk_bf16_f32 v230, v230, v231
	v_cvt_pk_bf16_f32 v231, v232, v233
	v_cvt_pk_bf16_f32 v232, v234, v235
	v_cvt_pk_bf16_f32 v233, v236, v237
	global_store_dwordx4 v164, v[230:233], s[0:1]
	s_waitcnt lgkmcnt(0)
	v_cvt_pk_bf16_f32 v238, v238, v239
	v_cvt_pk_bf16_f32 v239, v240, v241
	v_cvt_pk_bf16_f32 v240, v242, v243
	v_cvt_pk_bf16_f32 v241, v244, v245
	v_add_u32_e32 v164, 0x20000, v164
	global_store_dwordx4 v164, v[238:241], s[0:1]
	s_branch .LBB0_101
